# experiment: all s_setprio flips removed from the GEMM main loops
# baseline (speedup 1.0000x reference)
; #define PG8_STAGE(bufoff, gbase, voff) do { _Pragma("unroll") for (int _i = 0; _i < 2; ++_i) \
;         __builtin_amdgcn_global_load_lds((const unsigned*)((const char*)(gbase) + (voff)[_i]), (LAS unsigned*)(lds + (bufoff) + ldsw + _i * 8192), 16, 0, 0); } while (0)
; #define PG8_LDA(dst, b, h) do { _Pragma("unroll") for (int m = 0; m < 4; ++m) _Pragma("unroll") for (int k = 0; k < 2; ++k) dst[m][k] = *(const LAS bf16x8*)(lds + PG8_SA(b, h) + aoff + m * 2048 + k * 1024); } while (0)
; #define PG8_LDB(dst, b, h) do { _Pragma("unroll") for (int n = 0; n < 2; ++n) _Pragma("unroll") for (int k = 0; k < 2; ++k) dst[n][k] = *(const LAS bf16x8*)(lds + PG8_SB(b, h) + boff + n * 2048 + k * 1024); } while (0)
; #define PG8_MMA(ai, bj, At, Bt) do { __builtin_amdgcn_s_setprio(1); _Pragma("unroll") for (int m = 0; m < 4; ++m) _Pragma("unroll") for (int n = 0; n < 2; ++n) _Pragma("unroll") for (int k = 0; k < 2; ++k) \
;         acc[ai][bj][m][n] = __builtin_amdgcn_mfma_f32_16x16x32_bf16(Bt[n][k], At[m][k], acc[ai][bj][m][n], 0, 0, 0); __builtin_amdgcn_s_setprio(0); } while (0)
; #define PG8_WAIT_V(n) asm volatile("s_waitcnt vmcnt(" #n ")" ::: "memory")
; #define PG8_WAIT_L(n) asm volatile("s_waitcnt lgkmcnt(" #n ")" ::: "memory")
; #define PG8_BAR __builtin_amdgcn_s_barrier()
; #define PG8_SCHED __builtin_amdgcn_sched_barrier(0)
; template <class Epi>
; DI void gemm_phase(LAS unsigned char* lds, const Gemm g, const Order& S, const Epi& E, const int wv) {
;     ...
;         for (int t = 0; t < nt; t += 2) {
;             const bool last = (t == nt - 2);
;             const char* a1 = cA + (size_t)(t + 1) * kstep;
;             const char* a2 = last ? nA : cA + (size_t)(t + 2) * kstep; const char* b2 = last ? nB : cB + (size_t)(t + 2) * kstep;
;             const char* a3 = a2 + kstep; const char* b3 = b2 + kstep;
;             PG8_LDB(B0, 0, 0); PG8_LDB(B1, 0, 1); PG8_SCHED; PG8_LDA(At, 0, 0); PG8_STAGE(PG8_SA(1, 1), a1 + hstep, voffA);
;             PG8_WAIT_V(8); PG8_WAIT_L(0); PG8_BAR; PG8_MMA(0, 0, At, B0); PG8_MMA(0, 1, At, B1); PG8_BAR; PG8_SCHED;
;             PG8_LDA(At, 0, 1); PG8_STAGE(PG8_SB(0, 0), b2, voffB); PG8_STAGE(PG8_SB(0, 1), b2 + hstep, voffB); PG8_STAGE(PG8_SA(0, 0), a2, voffA);
;             PG8_WAIT_V(8); PG8_WAIT_L(0); PG8_BAR; PG8_MMA(1, 0, At, B0); PG8_MMA(1, 1, At, B1); PG8_BAR; PG8_SCHED;
.LBB0_155:
	s_add_u32 s12, s4, 0xfffc0080
	s_addc_u32 s13, s5, -1
	s_add_i32 s33, 0, 0x10000
	s_cmp_eq_u32 s31, 12
	s_cselect_b32 s15, s7, s13
	s_cselect_b32 s14, s27, s12
	v_add_u32_e32 v112, s33, v150
	s_cselect_b32 s13, s3, s30
	s_cselect_b32 s12, s28, s29
	s_add_i32 s36, 0, 0x14000
	ds_read_b128 v[142:145], v112
	ds_read_b128 v[156:159], v112 offset:1024
	ds_read_b128 v[160:163], v112 offset:2048
	ds_read_b128 v[164:167], v112 offset:3072
	v_add_u32_e32 v112, s36, v150
	ds_read_b128 v[168:171], v112
	ds_read_b128 v[172:175], v112 offset:1024
	ds_read_b128 v[176:179], v112 offset:2048
	ds_read_b128 v[180:183], v112 offset:3072
	v_lshl_add_u64 v[152:153], s[4:5], 0, v[138:139]
	s_add_i32 m0, s18, 0xc000
	ds_read_b128 v[184:187], v154
	ds_read_b128 v[204:207], v154 offset:1024
	ds_read_b128 v[208:211], v154 offset:2048
	ds_read_b128 v[212:215], v154 offset:3072
	ds_read_b128 v[216:219], v154 offset:4096
	ds_read_b128 v[220:223], v154 offset:5120
	ds_read_b128 v[224:227], v154 offset:6144
	ds_read_b128 v[228:231], v154 offset:7168
	global_load_lds_dwordx4 v[152:153], off
	v_lshl_add_u64 v[152:153], s[4:5], 0, v[140:141]
	s_add_i32 m0, s18, 0xe000
	s_nop 0
	global_load_lds_dwordx4 v[152:153], off
	s_waitcnt vmcnt(8)
	s_waitcnt lgkmcnt(0)
	s_barrier
	s_waitcnt lgkmcnt(0)
	v_mfma_f32_16x16x32_bf16 v[126:129], v[142:145], v[184:187], v[126:129]
	v_mfma_f32_16x16x32_bf16 v[122:125], v[160:163], v[184:187], v[122:125]
	v_mfma_f32_16x16x32_bf16 v[108:111], v[142:145], v[208:211], v[108:111]
	v_mfma_f32_16x16x32_bf16 v[104:107], v[160:163], v[208:211], v[104:107]
	v_mfma_f32_16x16x32_bf16 v[92:95], v[142:145], v[216:219], v[92:95]
	v_mfma_f32_16x16x32_bf16 v[88:91], v[160:163], v[216:219], v[88:91]
	v_mfma_f32_16x16x32_bf16 v[76:79], v[142:145], v[224:227], v[76:79]
	v_mfma_f32_16x16x32_bf16 v[72:75], v[160:163], v[224:227], v[72:75]
	v_mfma_f32_16x16x32_bf16 v[126:129], v[156:159], v[204:207], v[126:129]
	v_mfma_f32_16x16x32_bf16 v[122:125], v[164:167], v[204:207], v[122:125]
	v_mfma_f32_16x16x32_bf16 v[108:111], v[156:159], v[212:215], v[108:111]
	v_mfma_f32_16x16x32_bf16 v[104:107], v[164:167], v[212:215], v[104:107]
	v_mfma_f32_16x16x32_bf16 v[92:95], v[156:159], v[220:223], v[92:95]
	v_mfma_f32_16x16x32_bf16 v[88:91], v[164:167], v[220:223], v[88:91]
	v_mfma_f32_16x16x32_bf16 v[76:79], v[156:159], v[228:231], v[76:79]
	v_mfma_f32_16x16x32_bf16 v[72:75], v[164:167], v[228:231], v[72:75]
	v_mfma_f32_16x16x32_bf16 v[118:121], v[168:171], v[184:187], v[118:121]
	v_mfma_f32_16x16x32_bf16 v[114:117], v[176:179], v[184:187], v[114:117]
	v_mfma_f32_16x16x32_bf16 v[100:103], v[168:171], v[208:211], v[100:103]
	v_mfma_f32_16x16x32_bf16 v[96:99], v[176:179], v[208:211], v[96:99]
	v_mfma_f32_16x16x32_bf16 v[84:87], v[168:171], v[216:219], v[84:87]
	v_mfma_f32_16x16x32_bf16 v[80:83], v[176:179], v[216:219], v[80:83]
	v_mfma_f32_16x16x32_bf16 v[68:71], v[168:171], v[224:227], v[68:71]
	v_mfma_f32_16x16x32_bf16 v[64:67], v[176:179], v[224:227], v[64:67]
	v_mfma_f32_16x16x32_bf16 v[118:121], v[172:175], v[204:207], v[118:121]
	v_mfma_f32_16x16x32_bf16 v[114:117], v[180:183], v[204:207], v[114:117]
	v_mfma_f32_16x16x32_bf16 v[100:103], v[172:175], v[212:215], v[100:103]
	v_mfma_f32_16x16x32_bf16 v[96:99], v[180:183], v[212:215], v[96:99]
	v_mfma_f32_16x16x32_bf16 v[84:87], v[172:175], v[220:223], v[84:87]
	v_mfma_f32_16x16x32_bf16 v[80:83], v[180:183], v[220:223], v[80:83]
	v_mfma_f32_16x16x32_bf16 v[68:71], v[172:175], v[228:231], v[68:71]
	v_mfma_f32_16x16x32_bf16 v[64:67], v[180:183], v[228:231], v[64:67]
	s_barrier
	s_add_i32 s33, s33, s37
	v_lshl_add_u64 v[152:153], s[12:13], 0, v[134:135]
	s_mov_b32 m0, s33
	ds_read_b128 v[184:187], v154 offset:16384
	ds_read_b128 v[204:207], v154 offset:17408
	ds_read_b128 v[208:211], v154 offset:18432
	ds_read_b128 v[212:215], v154 offset:19456
	ds_read_b128 v[216:219], v154 offset:20480
	ds_read_b128 v[220:223], v154 offset:21504
	ds_read_b128 v[224:227], v154 offset:22528
	ds_read_b128 v[228:231], v154 offset:23552
	global_load_lds_dwordx4 v[152:153], off
	s_add_i32 m0, s33, 0x2000
	s_add_u32 s34, s12, 0x40000
	v_lshl_add_u64 v[188:189], s[12:13], 0, v[130:131]
	s_addc_u32 s35, s13, 0
	s_add_i32 s33, s36, s37
	global_load_lds_dwordx4 v[188:189], off
	v_lshl_add_u64 v[192:193], s[34:35], 0, v[134:135]
	s_mov_b32 m0, s33
	v_lshl_add_u64 v[194:195], s[14:15], 0, v[132:133]
	global_load_lds_dwordx4 v[192:193], off
	v_lshl_add_u64 v[192:193], s[34:35], 0, v[130:131]
	s_add_i32 m0, s33, 0x2000
	s_nop 0
	global_load_lds_dwordx4 v[192:193], off
	v_lshl_add_u64 v[192:193], s[14:15], 0, v[136:137]
	s_mov_b32 m0, s18
	s_nop 0
	global_load_lds_dwordx4 v[192:193], off
	s_mov_b32 m0, s19
	s_nop 0
	global_load_lds_dwordx4 v[194:195], off
	s_waitcnt vmcnt(8)
	s_waitcnt lgkmcnt(0)
	s_barrier
; #define PG8_STAGE(bufoff, gbase, voff) do { _Pragma("unroll") for (int _i = 0; _i < 2; ++_i) \
;         __builtin_amdgcn_global_load_lds((const unsigned*)((const char*)(gbase) + (voff)[_i]), (LAS unsigned*)(lds + (bufoff) + ldsw + _i * 8192), 16, 0, 0); } while (0)
; #define PG8_LDA(dst, b, h) do { _Pragma("unroll") for (int m = 0; m < 4; ++m) _Pragma("unroll") for (int k = 0; k < 2; ++k) dst[m][k] = *(const LAS bf16x8*)(lds + PG8_SA(b, h) + aoff + m * 2048 + k * 1024); } while (0)
; #define PG8_LDB(dst, b, h) do { _Pragma("unroll") for (int n = 0; n < 2; ++n) _Pragma("unroll") for (int k = 0; k < 2; ++k) dst[n][k] = *(const LAS bf16x8*)(lds + PG8_SB(b, h) + boff + n * 2048 + k * 1024); } while (0)
; #define PG8_MMA(ai, bj, At, Bt) do { __builtin_amdgcn_s_setprio(1); _Pragma("unroll") for (int m = 0; m < 4; ++m) _Pragma("unroll") for (int n = 0; n < 2; ++n) _Pragma("unroll") for (int k = 0; k < 2; ++k) \
;         acc[ai][bj][m][n] = __builtin_amdgcn_mfma_f32_16x16x32_bf16(Bt[n][k], At[m][k], acc[ai][bj][m][n], 0, 0, 0); __builtin_amdgcn_s_setprio(0); } while (0)
; #define PG8_WAIT_V(n) asm volatile("s_waitcnt vmcnt(" #n ")" ::: "memory")
; #define PG8_WAIT_L(n) asm volatile("s_waitcnt lgkmcnt(" #n ")" ::: "memory")
; #define PG8_BAR __builtin_amdgcn_s_barrier()
; #define PG8_SCHED __builtin_amdgcn_sched_barrier(0)
; template <class Epi>
; DI void gemm_phase(LAS unsigned char* lds, const Gemm g, const Order& S, const Epi& E, const int wv) {
;     ...
;             PG8_WAIT_V(8); PG8_WAIT_L(0); PG8_BAR; PG8_MMA(1, 0, At, B0); PG8_MMA(1, 1, At, B1); PG8_BAR; PG8_SCHED;
;             PG8_LDB(B0, 1, 0); PG8_LDB(B1, 1, 1); PG8_SCHED; PG8_LDA(At, 1, 0); PG8_STAGE(PG8_SA(0, 1), a2 + hstep, voffA);
;             PG8_WAIT_V(8); PG8_WAIT_L(0); PG8_BAR; PG8_MMA(0, 0, At, B0); PG8_MMA(0, 1, At, B1); PG8_BAR; PG8_SCHED;
	s_waitcnt lgkmcnt(0)
	v_mfma_f32_16x16x32_bf16 v[60:63], v[142:145], v[184:187], v[60:63]
	v_mfma_f32_16x16x32_bf16 v[56:59], v[160:163], v[184:187], v[56:59]
	v_mfma_f32_16x16x32_bf16 v[44:47], v[142:145], v[208:211], v[44:47]
	v_mfma_f32_16x16x32_bf16 v[40:43], v[160:163], v[208:211], v[40:43]
	v_mfma_f32_16x16x32_bf16 v[28:31], v[142:145], v[216:219], v[28:31]
	v_mfma_f32_16x16x32_bf16 v[24:27], v[160:163], v[216:219], v[24:27]
	v_mfma_f32_16x16x32_bf16 v[12:15], v[142:145], v[224:227], v[12:15]
	v_mfma_f32_16x16x32_bf16 v[8:11], v[160:163], v[224:227], v[8:11]
	v_mfma_f32_16x16x32_bf16 v[60:63], v[156:159], v[204:207], v[60:63]
	v_mfma_f32_16x16x32_bf16 v[56:59], v[164:167], v[204:207], v[56:59]
	v_mfma_f32_16x16x32_bf16 v[44:47], v[156:159], v[212:215], v[44:47]
	v_mfma_f32_16x16x32_bf16 v[40:43], v[164:167], v[212:215], v[40:43]
	v_mfma_f32_16x16x32_bf16 v[28:31], v[156:159], v[220:223], v[28:31]
	v_mfma_f32_16x16x32_bf16 v[24:27], v[164:167], v[220:223], v[24:27]
	v_mfma_f32_16x16x32_bf16 v[12:15], v[156:159], v[228:231], v[12:15]
	v_mfma_f32_16x16x32_bf16 v[8:11], v[164:167], v[228:231], v[8:11]
	v_mfma_f32_16x16x32_bf16 v[52:55], v[168:171], v[184:187], v[52:55]
	v_mfma_f32_16x16x32_bf16 v[48:51], v[176:179], v[184:187], v[48:51]
	v_mfma_f32_16x16x32_bf16 v[36:39], v[168:171], v[208:211], v[36:39]
	v_mfma_f32_16x16x32_bf16 v[32:35], v[176:179], v[208:211], v[32:35]
	v_mfma_f32_16x16x32_bf16 v[20:23], v[168:171], v[216:219], v[20:23]
	v_mfma_f32_16x16x32_bf16 v[16:19], v[176:179], v[216:219], v[16:19]
	v_mfma_f32_16x16x32_bf16 v[4:7], v[168:171], v[224:227], v[4:7]
	v_mfma_f32_16x16x32_bf16 v[0:3], v[176:179], v[224:227], v[0:3]
	v_mfma_f32_16x16x32_bf16 v[52:55], v[172:175], v[204:207], v[52:55]
	v_mfma_f32_16x16x32_bf16 v[48:51], v[180:183], v[204:207], v[48:51]
	v_mfma_f32_16x16x32_bf16 v[36:39], v[172:175], v[212:215], v[36:39]
	v_mfma_f32_16x16x32_bf16 v[32:35], v[180:183], v[212:215], v[32:35]
	v_mfma_f32_16x16x32_bf16 v[20:23], v[172:175], v[220:223], v[20:23]
	v_mfma_f32_16x16x32_bf16 v[16:19], v[180:183], v[220:223], v[16:19]
	v_mfma_f32_16x16x32_bf16 v[4:7], v[172:175], v[228:231], v[4:7]
	v_mfma_f32_16x16x32_bf16 v[0:3], v[180:183], v[228:231], v[0:3]
	s_barrier
	s_add_i32 s33, 0, 0x18000
	v_add_u32_e32 v112, s33, v150
	s_add_i32 s34, 0, 0x1c000
	ds_read_b128 v[142:145], v112
	ds_read_b128 v[156:159], v112 offset:1024
	ds_read_b128 v[160:163], v112 offset:2048
	ds_read_b128 v[164:167], v112 offset:3072
	v_add_u32_e32 v112, s34, v150
	ds_read_b128 v[168:171], v112
	ds_read_b128 v[172:175], v112 offset:1024
	ds_read_b128 v[176:179], v112 offset:2048
	ds_read_b128 v[180:183], v112 offset:3072
	s_add_u32 s14, s14, 0x40000
	s_addc_u32 s15, s15, 0
	s_mov_b32 m0, s20
	v_lshl_add_u64 v[196:197], s[14:15], 0, v[136:137]
	ds_read_b128 v[184:187], v154 offset:32768
	ds_read_b128 v[204:207], v154 offset:33792
	ds_read_b128 v[208:211], v154 offset:34816
	ds_read_b128 v[212:215], v154 offset:35840
	ds_read_b128 v[216:219], v154 offset:36864
	ds_read_b128 v[220:223], v154 offset:37888
	ds_read_b128 v[224:227], v154 offset:38912
	ds_read_b128 v[228:231], v154 offset:39936
	global_load_lds_dwordx4 v[196:197], off
	v_lshl_add_u64 v[196:197], s[14:15], 0, v[132:133]
	s_mov_b32 m0, s21
	s_nop 0
	global_load_lds_dwordx4 v[196:197], off
	s_waitcnt vmcnt(8)
	s_waitcnt lgkmcnt(0)
	s_barrier
	s_waitcnt lgkmcnt(0)
	v_mfma_f32_16x16x32_bf16 v[126:129], v[142:145], v[184:187], v[126:129]
	v_mfma_f32_16x16x32_bf16 v[122:125], v[160:163], v[184:187], v[122:125]
	v_mfma_f32_16x16x32_bf16 v[108:111], v[142:145], v[208:211], v[108:111]
	v_mfma_f32_16x16x32_bf16 v[104:107], v[160:163], v[208:211], v[104:107]
	v_mfma_f32_16x16x32_bf16 v[92:95], v[142:145], v[216:219], v[92:95]
	v_mfma_f32_16x16x32_bf16 v[88:91], v[160:163], v[216:219], v[88:91]
	v_mfma_f32_16x16x32_bf16 v[76:79], v[142:145], v[224:227], v[76:79]
	v_mfma_f32_16x16x32_bf16 v[72:75], v[160:163], v[224:227], v[72:75]
	v_mfma_f32_16x16x32_bf16 v[126:129], v[156:159], v[204:207], v[126:129]
	v_mfma_f32_16x16x32_bf16 v[122:125], v[164:167], v[204:207], v[122:125]
	v_mfma_f32_16x16x32_bf16 v[108:111], v[156:159], v[212:215], v[108:111]
	v_mfma_f32_16x16x32_bf16 v[104:107], v[164:167], v[212:215], v[104:107]
	v_mfma_f32_16x16x32_bf16 v[92:95], v[156:159], v[220:223], v[92:95]
	v_mfma_f32_16x16x32_bf16 v[88:91], v[164:167], v[220:223], v[88:91]
	v_mfma_f32_16x16x32_bf16 v[76:79], v[156:159], v[228:231], v[76:79]
	v_mfma_f32_16x16x32_bf16 v[72:75], v[164:167], v[228:231], v[72:75]
	v_mfma_f32_16x16x32_bf16 v[118:121], v[168:171], v[184:187], v[118:121]
	v_mfma_f32_16x16x32_bf16 v[114:117], v[176:179], v[184:187], v[114:117]
	v_mfma_f32_16x16x32_bf16 v[100:103], v[168:171], v[208:211], v[100:103]
	v_mfma_f32_16x16x32_bf16 v[96:99], v[176:179], v[208:211], v[96:99]
	v_mfma_f32_16x16x32_bf16 v[84:87], v[168:171], v[216:219], v[84:87]
	v_mfma_f32_16x16x32_bf16 v[80:83], v[176:179], v[216:219], v[80:83]
	v_mfma_f32_16x16x32_bf16 v[68:71], v[168:171], v[224:227], v[68:71]
	v_mfma_f32_16x16x32_bf16 v[64:67], v[176:179], v[224:227], v[64:67]
	v_mfma_f32_16x16x32_bf16 v[118:121], v[172:175], v[204:207], v[118:121]
	v_mfma_f32_16x16x32_bf16 v[114:117], v[180:183], v[204:207], v[114:117]
	v_mfma_f32_16x16x32_bf16 v[100:103], v[172:175], v[212:215], v[100:103]
	v_mfma_f32_16x16x32_bf16 v[96:99], v[180:183], v[212:215], v[96:99]
	v_mfma_f32_16x16x32_bf16 v[84:87], v[172:175], v[220:223], v[84:87]
	v_mfma_f32_16x16x32_bf16 v[80:83], v[180:183], v[220:223], v[80:83]
	v_mfma_f32_16x16x32_bf16 v[68:71], v[172:175], v[228:231], v[68:71]
	v_mfma_f32_16x16x32_bf16 v[64:67], v[180:183], v[228:231], v[64:67]
	s_barrier
; #define PG8_STAGE(bufoff, gbase, voff) do { _Pragma("unroll") for (int _i = 0; _i < 2; ++_i) \
;         __builtin_amdgcn_global_load_lds((const unsigned*)((const char*)(gbase) + (voff)[_i]), (LAS unsigned*)(lds + (bufoff) + ldsw + _i * 8192), 16, 0, 0); } while (0)
; #define PG8_LDA(dst, b, h) do { _Pragma("unroll") for (int m = 0; m < 4; ++m) _Pragma("unroll") for (int k = 0; k < 2; ++k) dst[m][k] = *(const LAS bf16x8*)(lds + PG8_SA(b, h) + aoff + m * 2048 + k * 1024); } while (0)
; #define PG8_MMA(ai, bj, At, Bt) do { __builtin_amdgcn_s_setprio(1); _Pragma("unroll") for (int m = 0; m < 4; ++m) _Pragma("unroll") for (int n = 0; n < 2; ++n) _Pragma("unroll") for (int k = 0; k < 2; ++k) \
;         acc[ai][bj][m][n] = __builtin_amdgcn_mfma_f32_16x16x32_bf16(Bt[n][k], At[m][k], acc[ai][bj][m][n], 0, 0, 0); __builtin_amdgcn_s_setprio(0); } while (0)
; #define PG8_WAIT_V(n) asm volatile("s_waitcnt vmcnt(" #n ")" ::: "memory")
; #define PG8_WAIT_L(n) asm volatile("s_waitcnt lgkmcnt(" #n ")" ::: "memory")
; #define PG8_BAR __builtin_amdgcn_s_barrier()
; #define PG8_SCHED __builtin_amdgcn_sched_barrier(0)
; template <class Epi>
; DI void gemm_phase(LAS unsigned char* lds, const Gemm g, const Order& S, const Epi& E, const int wv) {
;     ...
;             PG8_LDA(At, 1, 1); PG8_STAGE(PG8_SB(1, 0), b3, voffB); PG8_STAGE(PG8_SB(1, 1), b3 + hstep, voffB); PG8_STAGE(PG8_SA(1, 0), a3, voffA);
;             PG8_WAIT_V(8); PG8_WAIT_L(0); PG8_BAR; PG8_MMA(1, 0, At, B0); PG8_MMA(1, 1, At, B1); PG8_BAR; PG8_SCHED;
;         }
;         if (wr == 0) PG8_BAR;
	s_add_i32 s14, s33, s37
	v_lshl_add_u64 v[152:153], v[152:153], 0, s[38:39]
	s_mov_b32 m0, s14
	ds_read_b128 v[184:187], v154 offset:49152
	ds_read_b128 v[204:207], v154 offset:50176
	ds_read_b128 v[208:211], v154 offset:51200
	ds_read_b128 v[212:215], v154 offset:52224
	ds_read_b128 v[216:219], v154 offset:53248
	ds_read_b128 v[220:223], v154 offset:54272
	ds_read_b128 v[224:227], v154 offset:55296
	ds_read_b128 v[228:231], v154 offset:56320
	global_load_lds_dwordx4 v[152:153], off
	s_add_i32 m0, s14, 0x2000
	s_add_u32 s12, s12, 0x40080
	v_lshl_add_u64 v[152:153], v[188:189], 0, s[38:39]
	s_addc_u32 s13, s13, 0
	s_add_i32 s14, s34, s37
	global_load_lds_dwordx4 v[152:153], off
	v_lshl_add_u64 v[152:153], s[12:13], 0, v[134:135]
	s_mov_b32 m0, s14
	s_nop 0
	global_load_lds_dwordx4 v[152:153], off
	v_lshl_add_u64 v[152:153], s[12:13], 0, v[130:131]
	s_add_i32 m0, s14, 0x2000
	s_nop 0
	global_load_lds_dwordx4 v[152:153], off
	v_lshl_add_u64 v[152:153], v[192:193], 0, s[38:39]
	s_mov_b32 m0, s22
	s_nop 0
	global_load_lds_dwordx4 v[152:153], off
	v_lshl_add_u64 v[152:153], v[194:195], 0, s[38:39]
	s_mov_b32 m0, s23
	s_nop 0
	global_load_lds_dwordx4 v[152:153], off
	s_waitcnt vmcnt(8)
	s_waitcnt lgkmcnt(0)
	s_barrier
	s_waitcnt lgkmcnt(0)
	v_mfma_f32_16x16x32_bf16 v[60:63], v[142:145], v[184:187], v[60:63]
	v_mfma_f32_16x16x32_bf16 v[56:59], v[160:163], v[184:187], v[56:59]
	v_mfma_f32_16x16x32_bf16 v[44:47], v[142:145], v[208:211], v[44:47]
	v_mfma_f32_16x16x32_bf16 v[40:43], v[160:163], v[208:211], v[40:43]
	v_mfma_f32_16x16x32_bf16 v[28:31], v[142:145], v[216:219], v[28:31]
	v_mfma_f32_16x16x32_bf16 v[24:27], v[160:163], v[216:219], v[24:27]
	v_mfma_f32_16x16x32_bf16 v[12:15], v[142:145], v[224:227], v[12:15]
	v_mfma_f32_16x16x32_bf16 v[8:11], v[160:163], v[224:227], v[8:11]
	v_mfma_f32_16x16x32_bf16 v[60:63], v[156:159], v[204:207], v[60:63]
	v_mfma_f32_16x16x32_bf16 v[56:59], v[164:167], v[204:207], v[56:59]
	v_mfma_f32_16x16x32_bf16 v[44:47], v[156:159], v[212:215], v[44:47]
	v_mfma_f32_16x16x32_bf16 v[40:43], v[164:167], v[212:215], v[40:43]
	v_mfma_f32_16x16x32_bf16 v[28:31], v[156:159], v[220:223], v[28:31]
	v_mfma_f32_16x16x32_bf16 v[24:27], v[164:167], v[220:223], v[24:27]
	v_mfma_f32_16x16x32_bf16 v[12:15], v[156:159], v[228:231], v[12:15]
	v_mfma_f32_16x16x32_bf16 v[8:11], v[164:167], v[228:231], v[8:11]
	v_mfma_f32_16x16x32_bf16 v[52:55], v[168:171], v[184:187], v[52:55]
	v_mfma_f32_16x16x32_bf16 v[48:51], v[176:179], v[184:187], v[48:51]
	v_mfma_f32_16x16x32_bf16 v[36:39], v[168:171], v[208:211], v[36:39]
	v_mfma_f32_16x16x32_bf16 v[32:35], v[176:179], v[208:211], v[32:35]
	v_mfma_f32_16x16x32_bf16 v[20:23], v[168:171], v[216:219], v[20:23]
	v_mfma_f32_16x16x32_bf16 v[16:19], v[176:179], v[216:219], v[16:19]
	v_mfma_f32_16x16x32_bf16 v[4:7], v[168:171], v[224:227], v[4:7]
	v_mfma_f32_16x16x32_bf16 v[0:3], v[176:179], v[224:227], v[0:3]
	v_mfma_f32_16x16x32_bf16 v[52:55], v[172:175], v[204:207], v[52:55]
	v_mfma_f32_16x16x32_bf16 v[48:51], v[180:183], v[204:207], v[48:51]
	v_mfma_f32_16x16x32_bf16 v[36:39], v[172:175], v[212:215], v[36:39]
	v_mfma_f32_16x16x32_bf16 v[32:35], v[180:183], v[212:215], v[32:35]
	v_mfma_f32_16x16x32_bf16 v[20:23], v[172:175], v[220:223], v[20:23]
	v_mfma_f32_16x16x32_bf16 v[16:19], v[180:183], v[220:223], v[16:19]
	v_mfma_f32_16x16x32_bf16 v[4:7], v[172:175], v[228:231], v[4:7]
	v_mfma_f32_16x16x32_bf16 v[0:3], v[180:183], v[228:231], v[0:3]
	s_barrier
	s_add_i32 s31, s31, 2
	s_add_u32 s4, s4, 0x100
	s_addc_u32 s5, s5, 0
	s_add_u32 s29, s29, 0x100
	s_addc_u32 s30, s30, 0
	s_cmp_gt_u32 s31, 13
	s_cbranch_scc0 .LBB0_155
	v_readlane_b32 s4, v253, 24
	v_readlane_b32 s5, v253, 25
	v_readlane_b32 s28, v254, 47
	s_and_b64 vcc, exec, s[4:5]
	v_readlane_b32 s29, v254, 48
	s_cbranch_vccz .LBB0_158
	s_barrier

; #define PG8_STAGE(bufoff, gbase, voff) do { _Pragma("unroll") for (int _i = 0; _i < 2; ++_i) \
;         __builtin_amdgcn_global_load_lds((const unsigned*)((const char*)(gbase) + (voff)[_i]), (LAS unsigned*)(lds + (bufoff) + ldsw + _i * 8192), 16, 0, 0); } while (0)
; #define PG8_LDA(dst, b, h) do { _Pragma("unroll") for (int m = 0; m < 4; ++m) _Pragma("unroll") for (int k = 0; k < 2; ++k) dst[m][k] = *(const LAS bf16x8*)(lds + PG8_SA(b, h) + aoff + m * 2048 + k * 1024); } while (0)
; #define PG8_LDB(dst, b, h) do { _Pragma("unroll") for (int n = 0; n < 2; ++n) _Pragma("unroll") for (int k = 0; k < 2; ++k) dst[n][k] = *(const LAS bf16x8*)(lds + PG8_SB(b, h) + boff + n * 2048 + k * 1024); } while (0)
; #define PG8_MMA(ai, bj, At, Bt) do { __builtin_amdgcn_s_setprio(1); _Pragma("unroll") for (int m = 0; m < 4; ++m) _Pragma("unroll") for (int n = 0; n < 2; ++n) _Pragma("unroll") for (int k = 0; k < 2; ++k) \
;         acc[ai][bj][m][n] = __builtin_amdgcn_mfma_f32_16x16x32_bf16(Bt[n][k], At[m][k], acc[ai][bj][m][n], 0, 0, 0); __builtin_amdgcn_s_setprio(0); } while (0)
; #define PG8_WAIT_V(n) asm volatile("s_waitcnt vmcnt(" #n ")" ::: "memory")
; #define PG8_WAIT_L(n) asm volatile("s_waitcnt lgkmcnt(" #n ")" ::: "memory")
; #define PG8_BAR __builtin_amdgcn_s_barrier()
; #define PG8_SCHED __builtin_amdgcn_sched_barrier(0)
; template <class Epi>
; DI void gemm_phase(LAS unsigned char* lds, const Gemm g, const Order& S, const Epi& E, const int wv) {
;     ...
;         for (int t = 0; t < nt; t += 2) {
;             const bool last = (t == nt - 2);
;             const char* a1 = cA + (size_t)(t + 1) * kstep;
;             const char* a2 = last ? nA : cA + (size_t)(t + 2) * kstep; const char* b2 = last ? nB : cB + (size_t)(t + 2) * kstep;
;             const char* a3 = a2 + kstep; const char* b3 = b2 + kstep;
;             PG8_LDB(B0, 0, 0); PG8_LDB(B1, 0, 1); PG8_SCHED; PG8_LDA(At, 0, 0); PG8_STAGE(PG8_SA(1, 1), a1 + hstep, voffA);
;             PG8_WAIT_V(8); PG8_WAIT_L(0); PG8_BAR; PG8_MMA(0, 0, At, B0); PG8_MMA(0, 1, At, B1); PG8_BAR; PG8_SCHED;
;             PG8_LDA(At, 0, 1); PG8_STAGE(PG8_SB(0, 0), b2, voffB); PG8_STAGE(PG8_SB(0, 1), b2 + hstep, voffB); PG8_STAGE(PG8_SA(0, 0), a2, voffA);
;             PG8_WAIT_V(8); PG8_WAIT_L(0); PG8_BAR; PG8_MMA(1, 0, At, B0); PG8_MMA(1, 1, At, B1); PG8_BAR; PG8_SCHED;
.LBB0_699:
	s_add_i32 s49, s18, 2
	s_add_u32 s19, s16, 0xfffc0080
	s_addc_u32 s20, s17, -1
	s_add_i32 s50, 0, 0x10000
	s_cmp_eq_u32 s23, s18
	s_cselect_b32 s21, s1, s20
	s_cselect_b32 s20, s7, s19
	v_add_u32_e32 v149, s50, v150
	s_cselect_b32 s19, s5, s25
	s_cselect_b32 s18, s15, s24
	s_add_i32 s52, 0, 0x14000
	ds_read_b128 v[130:133], v149
	ds_read_b128 v[134:137], v149 offset:1024
	ds_read_b128 v[138:141], v149 offset:2048
	ds_read_b128 v[174:177], v149 offset:3072
	v_add_u32_e32 v149, s52, v150
	ds_read_b128 v[178:181], v149
	ds_read_b128 v[186:189], v149 offset:1024
	ds_read_b128 v[192:195], v149 offset:2048
	ds_read_b128 v[196:199], v149 offset:3072
	v_lshl_add_u64 v[152:153], s[16:17], 0, v[170:171]
	s_add_i32 m0, s30, 0xc000
	ds_read_b128 v[204:207], v185
	ds_read_b128 v[208:211], v185 offset:1024
	ds_read_b128 v[212:215], v185 offset:2048
	ds_read_b128 v[216:219], v185 offset:3072
	ds_read_b128 v[220:223], v185 offset:4096
	ds_read_b128 v[224:227], v185 offset:5120
	ds_read_b128 v[228:231], v185 offset:6144
	ds_read_b128 v[232:235], v185 offset:7168
	global_load_lds_dwordx4 v[152:153], off
	v_lshl_add_u64 v[152:153], s[16:17], 0, v[172:173]
	s_add_i32 m0, s30, 0xe000
	s_nop 0
	global_load_lds_dwordx4 v[152:153], off
	s_waitcnt vmcnt(8)
	s_waitcnt lgkmcnt(0)
	s_barrier
	s_waitcnt lgkmcnt(0)
	v_mfma_f32_16x16x32_bf16 v[126:129], v[130:133], v[204:207], v[126:129]
	v_mfma_f32_16x16x32_bf16 v[122:125], v[138:141], v[204:207], v[122:125]
	v_mfma_f32_16x16x32_bf16 v[118:121], v[130:133], v[212:215], v[118:121]
	v_mfma_f32_16x16x32_bf16 v[114:117], v[138:141], v[212:215], v[114:117]
	v_mfma_f32_16x16x32_bf16 v[108:111], v[130:133], v[220:223], v[108:111]
	v_mfma_f32_16x16x32_bf16 v[104:107], v[138:141], v[220:223], v[104:107]
	v_mfma_f32_16x16x32_bf16 v[100:103], v[130:133], v[228:231], v[100:103]
	v_mfma_f32_16x16x32_bf16 v[96:99], v[138:141], v[228:231], v[96:99]
	v_mfma_f32_16x16x32_bf16 v[126:129], v[134:137], v[208:211], v[126:129]
	v_mfma_f32_16x16x32_bf16 v[122:125], v[174:177], v[208:211], v[122:125]
	v_mfma_f32_16x16x32_bf16 v[118:121], v[134:137], v[216:219], v[118:121]
	v_mfma_f32_16x16x32_bf16 v[114:117], v[174:177], v[216:219], v[114:117]
	v_mfma_f32_16x16x32_bf16 v[108:111], v[134:137], v[224:227], v[108:111]
	v_mfma_f32_16x16x32_bf16 v[104:107], v[174:177], v[224:227], v[104:107]
	v_mfma_f32_16x16x32_bf16 v[100:103], v[134:137], v[232:235], v[100:103]
	v_mfma_f32_16x16x32_bf16 v[96:99], v[174:177], v[232:235], v[96:99]
	v_mfma_f32_16x16x32_bf16 v[60:63], v[178:181], v[204:207], v[60:63]
	v_mfma_f32_16x16x32_bf16 v[56:59], v[192:195], v[204:207], v[56:59]
	v_mfma_f32_16x16x32_bf16 v[52:55], v[178:181], v[212:215], v[52:55]
	v_mfma_f32_16x16x32_bf16 v[48:51], v[192:195], v[212:215], v[48:51]
	v_mfma_f32_16x16x32_bf16 v[44:47], v[178:181], v[220:223], v[44:47]
	v_mfma_f32_16x16x32_bf16 v[40:43], v[192:195], v[220:223], v[40:43]
	v_mfma_f32_16x16x32_bf16 v[36:39], v[178:181], v[228:231], v[36:39]
	v_mfma_f32_16x16x32_bf16 v[32:35], v[192:195], v[228:231], v[32:35]
	v_mfma_f32_16x16x32_bf16 v[60:63], v[186:189], v[208:211], v[60:63]
	v_mfma_f32_16x16x32_bf16 v[56:59], v[196:199], v[208:211], v[56:59]
	v_mfma_f32_16x16x32_bf16 v[52:55], v[186:189], v[216:219], v[52:55]
	v_mfma_f32_16x16x32_bf16 v[48:51], v[196:199], v[216:219], v[48:51]
	v_mfma_f32_16x16x32_bf16 v[44:47], v[186:189], v[224:227], v[44:47]
	v_mfma_f32_16x16x32_bf16 v[40:43], v[196:199], v[224:227], v[40:43]
	v_mfma_f32_16x16x32_bf16 v[36:39], v[186:189], v[232:235], v[36:39]
	v_mfma_f32_16x16x32_bf16 v[32:35], v[196:199], v[232:235], v[32:35]
	s_barrier
	s_add_i32 s50, s50, s53
	v_lshl_add_u64 v[152:153], s[18:19], 0, v[112:113]
	s_mov_b32 m0, s50
	ds_read_b128 v[204:207], v185 offset:16384
	ds_read_b128 v[208:211], v185 offset:17408
	ds_read_b128 v[212:215], v185 offset:18432
	ds_read_b128 v[216:219], v185 offset:19456
	ds_read_b128 v[220:223], v185 offset:20480
	ds_read_b128 v[224:227], v185 offset:21504
	ds_read_b128 v[228:231], v185 offset:22528
	ds_read_b128 v[232:235], v185 offset:23552
	global_load_lds_dwordx4 v[152:153], off
	s_add_i32 m0, s50, 0x2000
	s_add_u32 s50, s18, 0x40000
	v_lshl_add_u64 v[182:183], s[18:19], 0, v[146:147]
	s_addc_u32 s51, s19, 0
	s_add_i32 s52, s52, s53
	global_load_lds_dwordx4 v[182:183], off
	v_lshl_add_u64 v[236:237], s[50:51], 0, v[112:113]
	s_mov_b32 m0, s52
	v_lshl_add_u64 v[238:239], s[20:21], 0, v[144:145]
	global_load_lds_dwordx4 v[236:237], off
	v_lshl_add_u64 v[236:237], s[50:51], 0, v[146:147]
	s_add_i32 m0, s52, 0x2000
	s_nop 0
	global_load_lds_dwordx4 v[236:237], off
	v_lshl_add_u64 v[236:237], s[20:21], 0, v[142:143]
	s_mov_b32 m0, s30
	s_nop 0
	global_load_lds_dwordx4 v[236:237], off
	s_mov_b32 m0, s31
	s_nop 0
	global_load_lds_dwordx4 v[238:239], off
	s_waitcnt vmcnt(8)
	s_waitcnt lgkmcnt(0)
	s_barrier
; #define PG8_STAGE(bufoff, gbase, voff) do { _Pragma("unroll") for (int _i = 0; _i < 2; ++_i) \
;         __builtin_amdgcn_global_load_lds((const unsigned*)((const char*)(gbase) + (voff)[_i]), (LAS unsigned*)(lds + (bufoff) + ldsw + _i * 8192), 16, 0, 0); } while (0)
; #define PG8_LDA(dst, b, h) do { _Pragma("unroll") for (int m = 0; m < 4; ++m) _Pragma("unroll") for (int k = 0; k < 2; ++k) dst[m][k] = *(const LAS bf16x8*)(lds + PG8_SA(b, h) + aoff + m * 2048 + k * 1024); } while (0)
; #define PG8_LDB(dst, b, h) do { _Pragma("unroll") for (int n = 0; n < 2; ++n) _Pragma("unroll") for (int k = 0; k < 2; ++k) dst[n][k] = *(const LAS bf16x8*)(lds + PG8_SB(b, h) + boff + n * 2048 + k * 1024); } while (0)
; #define PG8_MMA(ai, bj, At, Bt) do { __builtin_amdgcn_s_setprio(1); _Pragma("unroll") for (int m = 0; m < 4; ++m) _Pragma("unroll") for (int n = 0; n < 2; ++n) _Pragma("unroll") for (int k = 0; k < 2; ++k) \
;         acc[ai][bj][m][n] = __builtin_amdgcn_mfma_f32_16x16x32_bf16(Bt[n][k], At[m][k], acc[ai][bj][m][n], 0, 0, 0); __builtin_amdgcn_s_setprio(0); } while (0)
; #define PG8_WAIT_V(n) asm volatile("s_waitcnt vmcnt(" #n ")" ::: "memory")
; #define PG8_WAIT_L(n) asm volatile("s_waitcnt lgkmcnt(" #n ")" ::: "memory")
; #define PG8_BAR __builtin_amdgcn_s_barrier()
; #define PG8_SCHED __builtin_amdgcn_sched_barrier(0)
; template <class Epi>
; DI void gemm_phase(LAS unsigned char* lds, const Gemm g, const Order& S, const Epi& E, const int wv) {
;     ...
;             PG8_WAIT_V(8); PG8_WAIT_L(0); PG8_BAR; PG8_MMA(1, 0, At, B0); PG8_MMA(1, 1, At, B1); PG8_BAR; PG8_SCHED;
;             PG8_LDB(B0, 1, 0); PG8_LDB(B1, 1, 1); PG8_SCHED; PG8_LDA(At, 1, 0); PG8_STAGE(PG8_SA(0, 1), a2 + hstep, voffA);
;             PG8_WAIT_V(8); PG8_WAIT_L(0); PG8_BAR; PG8_MMA(0, 0, At, B0); PG8_MMA(0, 1, At, B1); PG8_BAR; PG8_SCHED;
	s_waitcnt lgkmcnt(0)
	v_mfma_f32_16x16x32_bf16 v[92:95], v[130:133], v[204:207], v[92:95]
	v_mfma_f32_16x16x32_bf16 v[88:91], v[138:141], v[204:207], v[88:91]
	v_mfma_f32_16x16x32_bf16 v[84:87], v[130:133], v[212:215], v[84:87]
	v_mfma_f32_16x16x32_bf16 v[80:83], v[138:141], v[212:215], v[80:83]
	v_mfma_f32_16x16x32_bf16 v[76:79], v[130:133], v[220:223], v[76:79]
	v_mfma_f32_16x16x32_bf16 v[72:75], v[138:141], v[220:223], v[72:75]
	v_mfma_f32_16x16x32_bf16 v[68:71], v[130:133], v[228:231], v[68:71]
	v_mfma_f32_16x16x32_bf16 v[64:67], v[138:141], v[228:231], v[64:67]
	v_mfma_f32_16x16x32_bf16 v[92:95], v[134:137], v[208:211], v[92:95]
	v_mfma_f32_16x16x32_bf16 v[88:91], v[174:177], v[208:211], v[88:91]
	v_mfma_f32_16x16x32_bf16 v[84:87], v[134:137], v[216:219], v[84:87]
	v_mfma_f32_16x16x32_bf16 v[80:83], v[174:177], v[216:219], v[80:83]
	v_mfma_f32_16x16x32_bf16 v[76:79], v[134:137], v[224:227], v[76:79]
	v_mfma_f32_16x16x32_bf16 v[72:75], v[174:177], v[224:227], v[72:75]
	v_mfma_f32_16x16x32_bf16 v[68:71], v[134:137], v[232:235], v[68:71]
	v_mfma_f32_16x16x32_bf16 v[64:67], v[174:177], v[232:235], v[64:67]
	v_mfma_f32_16x16x32_bf16 v[28:31], v[178:181], v[204:207], v[28:31]
	v_mfma_f32_16x16x32_bf16 v[24:27], v[192:195], v[204:207], v[24:27]
	v_mfma_f32_16x16x32_bf16 v[20:23], v[178:181], v[212:215], v[20:23]
	v_mfma_f32_16x16x32_bf16 v[16:19], v[192:195], v[212:215], v[16:19]
	v_mfma_f32_16x16x32_bf16 v[12:15], v[178:181], v[220:223], v[12:15]
	v_mfma_f32_16x16x32_bf16 v[8:11], v[192:195], v[220:223], v[8:11]
	v_mfma_f32_16x16x32_bf16 v[4:7], v[178:181], v[228:231], v[4:7]
	v_mfma_f32_16x16x32_bf16 v[0:3], v[192:195], v[228:231], v[0:3]
	v_mfma_f32_16x16x32_bf16 v[28:31], v[186:189], v[208:211], v[28:31]
	v_mfma_f32_16x16x32_bf16 v[24:27], v[196:199], v[208:211], v[24:27]
	v_mfma_f32_16x16x32_bf16 v[20:23], v[186:189], v[216:219], v[20:23]
	v_mfma_f32_16x16x32_bf16 v[16:19], v[196:199], v[216:219], v[16:19]
	v_mfma_f32_16x16x32_bf16 v[12:15], v[186:189], v[224:227], v[12:15]
	v_mfma_f32_16x16x32_bf16 v[8:11], v[196:199], v[224:227], v[8:11]
	v_mfma_f32_16x16x32_bf16 v[4:7], v[186:189], v[232:235], v[4:7]
	v_mfma_f32_16x16x32_bf16 v[0:3], v[196:199], v[232:235], v[0:3]
	s_barrier
	s_add_i32 s50, 0, 0x18000
	v_add_u32_e32 v149, s50, v150
	s_add_i32 s51, 0, 0x1c000
	ds_read_b128 v[130:133], v149
	ds_read_b128 v[134:137], v149 offset:1024
	ds_read_b128 v[138:141], v149 offset:2048
	ds_read_b128 v[174:177], v149 offset:3072
	v_add_u32_e32 v149, s51, v150
	ds_read_b128 v[178:181], v149
	ds_read_b128 v[186:189], v149 offset:1024
	ds_read_b128 v[192:195], v149 offset:2048
	ds_read_b128 v[196:199], v149 offset:3072
	s_add_u32 s20, s20, 0x40000
	s_addc_u32 s21, s21, 0
	s_mov_b32 m0, s33
	v_lshl_add_u64 v[240:241], s[20:21], 0, v[142:143]
	ds_read_b128 v[204:207], v185 offset:32768
	ds_read_b128 v[208:211], v185 offset:33792
	ds_read_b128 v[212:215], v185 offset:34816
	ds_read_b128 v[216:219], v185 offset:35840
	ds_read_b128 v[220:223], v185 offset:36864
	ds_read_b128 v[224:227], v185 offset:37888
	ds_read_b128 v[228:231], v185 offset:38912
	ds_read_b128 v[232:235], v185 offset:39936
	global_load_lds_dwordx4 v[240:241], off
	v_lshl_add_u64 v[240:241], s[20:21], 0, v[144:145]
	s_mov_b32 m0, s34
	s_nop 0
	global_load_lds_dwordx4 v[240:241], off
	s_waitcnt vmcnt(8)
	s_waitcnt lgkmcnt(0)
	s_barrier
	s_waitcnt lgkmcnt(0)
	v_mfma_f32_16x16x32_bf16 v[126:129], v[130:133], v[204:207], v[126:129]
	v_mfma_f32_16x16x32_bf16 v[122:125], v[138:141], v[204:207], v[122:125]
	v_mfma_f32_16x16x32_bf16 v[118:121], v[130:133], v[212:215], v[118:121]
	v_mfma_f32_16x16x32_bf16 v[114:117], v[138:141], v[212:215], v[114:117]
	v_mfma_f32_16x16x32_bf16 v[108:111], v[130:133], v[220:223], v[108:111]
	v_mfma_f32_16x16x32_bf16 v[104:107], v[138:141], v[220:223], v[104:107]
	v_mfma_f32_16x16x32_bf16 v[100:103], v[130:133], v[228:231], v[100:103]
	v_mfma_f32_16x16x32_bf16 v[96:99], v[138:141], v[228:231], v[96:99]
	v_mfma_f32_16x16x32_bf16 v[126:129], v[134:137], v[208:211], v[126:129]
	v_mfma_f32_16x16x32_bf16 v[122:125], v[174:177], v[208:211], v[122:125]
	v_mfma_f32_16x16x32_bf16 v[118:121], v[134:137], v[216:219], v[118:121]
	v_mfma_f32_16x16x32_bf16 v[114:117], v[174:177], v[216:219], v[114:117]
	v_mfma_f32_16x16x32_bf16 v[108:111], v[134:137], v[224:227], v[108:111]
	v_mfma_f32_16x16x32_bf16 v[104:107], v[174:177], v[224:227], v[104:107]
	v_mfma_f32_16x16x32_bf16 v[100:103], v[134:137], v[232:235], v[100:103]
	v_mfma_f32_16x16x32_bf16 v[96:99], v[174:177], v[232:235], v[96:99]
	v_mfma_f32_16x16x32_bf16 v[60:63], v[178:181], v[204:207], v[60:63]
	v_mfma_f32_16x16x32_bf16 v[56:59], v[192:195], v[204:207], v[56:59]
	v_mfma_f32_16x16x32_bf16 v[52:55], v[178:181], v[212:215], v[52:55]
	v_mfma_f32_16x16x32_bf16 v[48:51], v[192:195], v[212:215], v[48:51]
	v_mfma_f32_16x16x32_bf16 v[44:47], v[178:181], v[220:223], v[44:47]
	v_mfma_f32_16x16x32_bf16 v[40:43], v[192:195], v[220:223], v[40:43]
	v_mfma_f32_16x16x32_bf16 v[36:39], v[178:181], v[228:231], v[36:39]
	v_mfma_f32_16x16x32_bf16 v[32:35], v[192:195], v[228:231], v[32:35]
	v_mfma_f32_16x16x32_bf16 v[60:63], v[186:189], v[208:211], v[60:63]
	v_mfma_f32_16x16x32_bf16 v[56:59], v[196:199], v[208:211], v[56:59]
	v_mfma_f32_16x16x32_bf16 v[52:55], v[186:189], v[216:219], v[52:55]
	v_mfma_f32_16x16x32_bf16 v[48:51], v[196:199], v[216:219], v[48:51]
	v_mfma_f32_16x16x32_bf16 v[44:47], v[186:189], v[224:227], v[44:47]
	v_mfma_f32_16x16x32_bf16 v[40:43], v[196:199], v[224:227], v[40:43]
	v_mfma_f32_16x16x32_bf16 v[36:39], v[186:189], v[232:235], v[36:39]
	v_mfma_f32_16x16x32_bf16 v[32:35], v[196:199], v[232:235], v[32:35]
	s_barrier
; #define PG8_STAGE(bufoff, gbase, voff) do { _Pragma("unroll") for (int _i = 0; _i < 2; ++_i) \
;         __builtin_amdgcn_global_load_lds((const unsigned*)((const char*)(gbase) + (voff)[_i]), (LAS unsigned*)(lds + (bufoff) + ldsw + _i * 8192), 16, 0, 0); } while (0)
; #define PG8_LDA(dst, b, h) do { _Pragma("unroll") for (int m = 0; m < 4; ++m) _Pragma("unroll") for (int k = 0; k < 2; ++k) dst[m][k] = *(const LAS bf16x8*)(lds + PG8_SA(b, h) + aoff + m * 2048 + k * 1024); } while (0)
; #define PG8_MMA(ai, bj, At, Bt) do { __builtin_amdgcn_s_setprio(1); _Pragma("unroll") for (int m = 0; m < 4; ++m) _Pragma("unroll") for (int n = 0; n < 2; ++n) _Pragma("unroll") for (int k = 0; k < 2; ++k) \
;         acc[ai][bj][m][n] = __builtin_amdgcn_mfma_f32_16x16x32_bf16(Bt[n][k], At[m][k], acc[ai][bj][m][n], 0, 0, 0); __builtin_amdgcn_s_setprio(0); } while (0)
; #define PG8_WAIT_V(n) asm volatile("s_waitcnt vmcnt(" #n ")" ::: "memory")
; #define PG8_WAIT_L(n) asm volatile("s_waitcnt lgkmcnt(" #n ")" ::: "memory")
; #define PG8_BAR __builtin_amdgcn_s_barrier()
; #define PG8_SCHED __builtin_amdgcn_sched_barrier(0)
; template <class Epi>
; DI void gemm_phase(LAS unsigned char* lds, const Gemm g, const Order& S, const Epi& E, const int wv) {
;     ...
;             PG8_LDA(At, 1, 1); PG8_STAGE(PG8_SB(1, 0), b3, voffB); PG8_STAGE(PG8_SB(1, 1), b3 + hstep, voffB); PG8_STAGE(PG8_SA(1, 0), a3, voffA);
;             PG8_WAIT_V(8); PG8_WAIT_L(0); PG8_BAR; PG8_MMA(1, 0, At, B0); PG8_MMA(1, 1, At, B1); PG8_BAR; PG8_SCHED;
;         }
;         if (wr == 0) PG8_BAR;
	s_add_i32 s20, s50, s53
	v_lshl_add_u64 v[152:153], v[152:153], 0, s[54:55]
	s_mov_b32 m0, s20
	ds_read_b128 v[204:207], v185 offset:49152
	ds_read_b128 v[208:211], v185 offset:50176
	ds_read_b128 v[212:215], v185 offset:51200
	ds_read_b128 v[216:219], v185 offset:52224
	ds_read_b128 v[220:223], v185 offset:53248
	ds_read_b128 v[224:227], v185 offset:54272
	ds_read_b128 v[228:231], v185 offset:55296
	ds_read_b128 v[232:235], v185 offset:56320
	global_load_lds_dwordx4 v[152:153], off
	s_add_i32 m0, s20, 0x2000
	s_add_u32 s18, s18, 0x40080
	v_lshl_add_u64 v[152:153], v[182:183], 0, s[54:55]
	s_addc_u32 s19, s19, 0
	s_add_i32 s20, s51, s53
	global_load_lds_dwordx4 v[152:153], off
	v_lshl_add_u64 v[152:153], s[18:19], 0, v[112:113]
	s_mov_b32 m0, s20
	s_nop 0
	global_load_lds_dwordx4 v[152:153], off
	v_lshl_add_u64 v[152:153], s[18:19], 0, v[146:147]
	s_add_i32 m0, s20, 0x2000
	s_nop 0
	global_load_lds_dwordx4 v[152:153], off
	v_lshl_add_u64 v[152:153], v[236:237], 0, s[54:55]
	s_mov_b32 m0, s37
	s_nop 0
	global_load_lds_dwordx4 v[152:153], off
	v_lshl_add_u64 v[152:153], v[238:239], 0, s[54:55]
	s_mov_b32 m0, s40
	s_nop 0
	global_load_lds_dwordx4 v[152:153], off
	s_waitcnt vmcnt(8)
	s_waitcnt lgkmcnt(0)
	s_barrier
	s_waitcnt lgkmcnt(0)
	v_mfma_f32_16x16x32_bf16 v[92:95], v[130:133], v[204:207], v[92:95]
	v_mfma_f32_16x16x32_bf16 v[88:91], v[138:141], v[204:207], v[88:91]
	v_mfma_f32_16x16x32_bf16 v[84:87], v[130:133], v[212:215], v[84:87]
	v_mfma_f32_16x16x32_bf16 v[80:83], v[138:141], v[212:215], v[80:83]
	v_mfma_f32_16x16x32_bf16 v[76:79], v[130:133], v[220:223], v[76:79]
	v_mfma_f32_16x16x32_bf16 v[72:75], v[138:141], v[220:223], v[72:75]
	v_mfma_f32_16x16x32_bf16 v[68:71], v[130:133], v[228:231], v[68:71]
	v_mfma_f32_16x16x32_bf16 v[64:67], v[138:141], v[228:231], v[64:67]
	v_mfma_f32_16x16x32_bf16 v[92:95], v[134:137], v[208:211], v[92:95]
	v_mfma_f32_16x16x32_bf16 v[88:91], v[174:177], v[208:211], v[88:91]
	v_mfma_f32_16x16x32_bf16 v[84:87], v[134:137], v[216:219], v[84:87]
	v_mfma_f32_16x16x32_bf16 v[80:83], v[174:177], v[216:219], v[80:83]
	v_mfma_f32_16x16x32_bf16 v[76:79], v[134:137], v[224:227], v[76:79]
	v_mfma_f32_16x16x32_bf16 v[72:75], v[174:177], v[224:227], v[72:75]
	v_mfma_f32_16x16x32_bf16 v[68:71], v[134:137], v[232:235], v[68:71]
	v_mfma_f32_16x16x32_bf16 v[64:67], v[174:177], v[232:235], v[64:67]
	v_mfma_f32_16x16x32_bf16 v[28:31], v[178:181], v[204:207], v[28:31]
	v_mfma_f32_16x16x32_bf16 v[24:27], v[192:195], v[204:207], v[24:27]
	v_mfma_f32_16x16x32_bf16 v[20:23], v[178:181], v[212:215], v[20:23]
	v_mfma_f32_16x16x32_bf16 v[16:19], v[192:195], v[212:215], v[16:19]
	v_mfma_f32_16x16x32_bf16 v[12:15], v[178:181], v[220:223], v[12:15]
	v_mfma_f32_16x16x32_bf16 v[8:11], v[192:195], v[220:223], v[8:11]
	v_mfma_f32_16x16x32_bf16 v[4:7], v[178:181], v[228:231], v[4:7]
	v_mfma_f32_16x16x32_bf16 v[0:3], v[192:195], v[228:231], v[0:3]
	v_mfma_f32_16x16x32_bf16 v[28:31], v[186:189], v[208:211], v[28:31]
	v_mfma_f32_16x16x32_bf16 v[24:27], v[196:199], v[208:211], v[24:27]
	v_mfma_f32_16x16x32_bf16 v[20:23], v[186:189], v[216:219], v[20:23]
	v_mfma_f32_16x16x32_bf16 v[16:19], v[196:199], v[216:219], v[16:19]
	v_mfma_f32_16x16x32_bf16 v[12:15], v[186:189], v[224:227], v[12:15]
	v_mfma_f32_16x16x32_bf16 v[8:11], v[196:199], v[224:227], v[8:11]
	v_mfma_f32_16x16x32_bf16 v[4:7], v[186:189], v[232:235], v[4:7]
	v_mfma_f32_16x16x32_bf16 v[0:3], v[196:199], v[232:235], v[0:3]
	s_barrier
	s_add_u32 s16, s16, 0x100
	s_addc_u32 s17, s17, 0
	s_add_u32 s24, s24, 0x100
	s_addc_u32 s25, s25, 0
	s_cmp_ge_u32 s49, s22
	s_mov_b32 s18, s49
	s_cbranch_scc0 .LBB0_699
	v_readlane_b32 s16, v253, 24
	v_readlane_b32 s17, v253, 25
	s_and_b64 vcc, exec, s[16:17]
	s_cbranch_vccz .LBB0_702
	s_barrier

; #define PG8_STAGE(bufoff, gbase, voff) do { _Pragma("unroll") for (int _i = 0; _i < 2; ++_i) \
;         __builtin_amdgcn_global_load_lds((const unsigned*)((const char*)(gbase) + (voff)[_i]), (LAS unsigned*)(lds + (bufoff) + ldsw + _i * 8192), 16, 0, 0); } while (0)
; #define PG8_LDA(dst, b, h) do { _Pragma("unroll") for (int m = 0; m < 4; ++m) _Pragma("unroll") for (int k = 0; k < 2; ++k) dst[m][k] = *(const LAS bf16x8*)(lds + PG8_SA(b, h) + aoff + m * 2048 + k * 1024); } while (0)
; #define PG8_LDB(dst, b, h) do { _Pragma("unroll") for (int n = 0; n < 2; ++n) _Pragma("unroll") for (int k = 0; k < 2; ++k) dst[n][k] = *(const LAS bf16x8*)(lds + PG8_SB(b, h) + boff + n * 2048 + k * 1024); } while (0)
; #define PG8_MMA(ai, bj, At, Bt) do { __builtin_amdgcn_s_setprio(1); _Pragma("unroll") for (int m = 0; m < 4; ++m) _Pragma("unroll") for (int n = 0; n < 2; ++n) _Pragma("unroll") for (int k = 0; k < 2; ++k) \
;         acc[ai][bj][m][n] = __builtin_amdgcn_mfma_f32_16x16x32_bf16(Bt[n][k], At[m][k], acc[ai][bj][m][n], 0, 0, 0); __builtin_amdgcn_s_setprio(0); } while (0)
; #define PG8_WAIT_V(n) asm volatile("s_waitcnt vmcnt(" #n ")" ::: "memory")
; #define PG8_WAIT_L(n) asm volatile("s_waitcnt lgkmcnt(" #n ")" ::: "memory")
; #define PG8_BAR __builtin_amdgcn_s_barrier()
; #define PG8_SCHED __builtin_amdgcn_sched_barrier(0)
; template <class Epi>
; DI void gemm_phase(LAS unsigned char* lds, const Gemm g, const Order& S, const Epi& E, const int wv) {
;     ...
;         for (int t = 0; t < nt; t += 2) {
;             const bool last = (t == nt - 2);
;             const char* a1 = cA + (size_t)(t + 1) * kstep;
;             const char* a2 = last ? nA : cA + (size_t)(t + 2) * kstep; const char* b2 = last ? nB : cB + (size_t)(t + 2) * kstep;
;             const char* a3 = a2 + kstep; const char* b3 = b2 + kstep;
;             PG8_LDB(B0, 0, 0); PG8_LDB(B1, 0, 1); PG8_SCHED; PG8_LDA(At, 0, 0); PG8_STAGE(PG8_SA(1, 1), a1 + hstep, voffA);
;             PG8_WAIT_V(8); PG8_WAIT_L(0); PG8_BAR; PG8_MMA(0, 0, At, B0); PG8_MMA(0, 1, At, B1); PG8_BAR; PG8_SCHED;
;             PG8_LDA(At, 0, 1); PG8_STAGE(PG8_SB(0, 0), b2, voffB); PG8_STAGE(PG8_SB(0, 1), b2 + hstep, voffB); PG8_STAGE(PG8_SA(0, 0), a2, voffA);
;             PG8_WAIT_V(8); PG8_WAIT_L(0); PG8_BAR; PG8_MMA(1, 0, At, B0); PG8_MMA(1, 1, At, B1); PG8_BAR; PG8_SCHED;
.LBB0_908:
	s_add_u32 s18, s16, 0xfffc0080
	s_addc_u32 s19, s17, -1
	s_add_i32 s43, 0, 0x10000
	s_cmp_eq_u32 s42, 12
	s_cselect_b32 s21, s9, s19
	s_cselect_b32 s20, s36, s18
	v_add_u32_e32 v149, s43, v141
	s_cselect_b32 s19, s3, s41
	s_cselect_b32 s18, s37, s40
	s_add_i32 s46, 0, 0x14000
	ds_read_b128 v[144:147], v149
	ds_read_b128 v[152:155], v149 offset:1024
	ds_read_b128 v[156:159], v149 offset:2048
	ds_read_b128 v[160:163], v149 offset:3072
	v_add_u32_e32 v149, s46, v141
	ds_read_b128 v[164:167], v149
	ds_read_b128 v[168:171], v149 offset:1024
	ds_read_b128 v[172:175], v149 offset:2048
	ds_read_b128 v[176:179], v149 offset:3072
	v_lshl_add_u64 v[188:189], s[16:17], 0, v[136:137]
	s_add_i32 m0, s15, 0xc000
	ds_read_b128 v[180:183], v143
	ds_read_b128 v[184:187], v143 offset:1024
	ds_read_b128 v[192:195], v143 offset:2048
	ds_read_b128 v[196:199], v143 offset:3072
	ds_read_b128 v[204:207], v143 offset:4096
	ds_read_b128 v[208:211], v143 offset:5120
	ds_read_b128 v[212:215], v143 offset:6144
	ds_read_b128 v[216:219], v143 offset:7168
	global_load_lds_dwordx4 v[188:189], off
	v_lshl_add_u64 v[188:189], s[16:17], 0, v[138:139]
	s_add_i32 m0, s15, 0xe000
	s_nop 0
	global_load_lds_dwordx4 v[188:189], off
	s_waitcnt vmcnt(8)
	s_waitcnt lgkmcnt(0)
	s_barrier
	s_waitcnt lgkmcnt(0)
	v_mfma_f32_16x16x32_bf16 v[126:129], v[144:147], v[180:183], v[126:129]
	v_mfma_f32_16x16x32_bf16 v[122:125], v[156:159], v[180:183], v[122:125]
	v_mfma_f32_16x16x32_bf16 v[108:111], v[144:147], v[192:195], v[108:111]
	v_mfma_f32_16x16x32_bf16 v[104:107], v[156:159], v[192:195], v[104:107]
	v_mfma_f32_16x16x32_bf16 v[92:95], v[144:147], v[204:207], v[92:95]
	v_mfma_f32_16x16x32_bf16 v[88:91], v[156:159], v[204:207], v[88:91]
	v_mfma_f32_16x16x32_bf16 v[76:79], v[144:147], v[212:215], v[76:79]
	v_mfma_f32_16x16x32_bf16 v[72:75], v[156:159], v[212:215], v[72:75]
	v_mfma_f32_16x16x32_bf16 v[126:129], v[152:155], v[184:187], v[126:129]
	v_mfma_f32_16x16x32_bf16 v[122:125], v[160:163], v[184:187], v[122:125]
	v_mfma_f32_16x16x32_bf16 v[108:111], v[152:155], v[196:199], v[108:111]
	v_mfma_f32_16x16x32_bf16 v[104:107], v[160:163], v[196:199], v[104:107]
	v_mfma_f32_16x16x32_bf16 v[92:95], v[152:155], v[208:211], v[92:95]
	v_mfma_f32_16x16x32_bf16 v[88:91], v[160:163], v[208:211], v[88:91]
	v_mfma_f32_16x16x32_bf16 v[76:79], v[152:155], v[216:219], v[76:79]
	v_mfma_f32_16x16x32_bf16 v[72:75], v[160:163], v[216:219], v[72:75]
	v_mfma_f32_16x16x32_bf16 v[118:121], v[164:167], v[180:183], v[118:121]
	v_mfma_f32_16x16x32_bf16 v[114:117], v[172:175], v[180:183], v[114:117]
	v_mfma_f32_16x16x32_bf16 v[100:103], v[164:167], v[192:195], v[100:103]
	v_mfma_f32_16x16x32_bf16 v[96:99], v[172:175], v[192:195], v[96:99]
	v_mfma_f32_16x16x32_bf16 v[84:87], v[164:167], v[204:207], v[84:87]
	v_mfma_f32_16x16x32_bf16 v[80:83], v[172:175], v[204:207], v[80:83]
	v_mfma_f32_16x16x32_bf16 v[68:71], v[164:167], v[212:215], v[68:71]
	v_mfma_f32_16x16x32_bf16 v[64:67], v[172:175], v[212:215], v[64:67]
	v_mfma_f32_16x16x32_bf16 v[118:121], v[168:171], v[184:187], v[118:121]
	v_mfma_f32_16x16x32_bf16 v[114:117], v[176:179], v[184:187], v[114:117]
	v_mfma_f32_16x16x32_bf16 v[100:103], v[168:171], v[196:199], v[100:103]
	v_mfma_f32_16x16x32_bf16 v[96:99], v[176:179], v[196:199], v[96:99]
	v_mfma_f32_16x16x32_bf16 v[84:87], v[168:171], v[208:211], v[84:87]
	v_mfma_f32_16x16x32_bf16 v[80:83], v[176:179], v[208:211], v[80:83]
	v_mfma_f32_16x16x32_bf16 v[68:71], v[168:171], v[216:219], v[68:71]
	v_mfma_f32_16x16x32_bf16 v[64:67], v[176:179], v[216:219], v[64:67]
	s_barrier
	s_add_i32 s43, s43, s47
	v_lshl_add_u64 v[188:189], s[18:19], 0, v[112:113]
	s_mov_b32 m0, s43
	ds_read_b128 v[180:183], v143 offset:16384
	ds_read_b128 v[184:187], v143 offset:17408
	ds_read_b128 v[192:195], v143 offset:18432
	ds_read_b128 v[196:199], v143 offset:19456
	ds_read_b128 v[204:207], v143 offset:20480
	ds_read_b128 v[208:211], v143 offset:21504
	ds_read_b128 v[212:215], v143 offset:22528
	ds_read_b128 v[216:219], v143 offset:23552
	global_load_lds_dwordx4 v[188:189], off
	s_add_i32 m0, s43, 0x2000
	s_add_u32 s44, s18, 0x40000
	v_lshl_add_u64 v[220:221], s[18:19], 0, v[134:135]
	s_addc_u32 s45, s19, 0
	s_add_i32 s43, s46, s47
	global_load_lds_dwordx4 v[220:221], off
	v_lshl_add_u64 v[222:223], s[44:45], 0, v[112:113]
	s_mov_b32 m0, s43
	v_lshl_add_u64 v[224:225], s[20:21], 0, v[132:133]
	global_load_lds_dwordx4 v[222:223], off
	v_lshl_add_u64 v[222:223], s[44:45], 0, v[134:135]
	s_add_i32 m0, s43, 0x2000
	s_nop 0
	global_load_lds_dwordx4 v[222:223], off
	v_lshl_add_u64 v[222:223], s[20:21], 0, v[130:131]
	s_mov_b32 m0, s15
	s_nop 0
	global_load_lds_dwordx4 v[222:223], off
	s_mov_b32 m0, s28
	s_nop 0
	global_load_lds_dwordx4 v[224:225], off
	s_waitcnt vmcnt(8)
	s_waitcnt lgkmcnt(0)
	s_barrier
; #define PG8_STAGE(bufoff, gbase, voff) do { _Pragma("unroll") for (int _i = 0; _i < 2; ++_i) \
;         __builtin_amdgcn_global_load_lds((const unsigned*)((const char*)(gbase) + (voff)[_i]), (LAS unsigned*)(lds + (bufoff) + ldsw + _i * 8192), 16, 0, 0); } while (0)
; #define PG8_LDA(dst, b, h) do { _Pragma("unroll") for (int m = 0; m < 4; ++m) _Pragma("unroll") for (int k = 0; k < 2; ++k) dst[m][k] = *(const LAS bf16x8*)(lds + PG8_SA(b, h) + aoff + m * 2048 + k * 1024); } while (0)
; #define PG8_LDB(dst, b, h) do { _Pragma("unroll") for (int n = 0; n < 2; ++n) _Pragma("unroll") for (int k = 0; k < 2; ++k) dst[n][k] = *(const LAS bf16x8*)(lds + PG8_SB(b, h) + boff + n * 2048 + k * 1024); } while (0)
; #define PG8_MMA(ai, bj, At, Bt) do { __builtin_amdgcn_s_setprio(1); _Pragma("unroll") for (int m = 0; m < 4; ++m) _Pragma("unroll") for (int n = 0; n < 2; ++n) _Pragma("unroll") for (int k = 0; k < 2; ++k) \
;         acc[ai][bj][m][n] = __builtin_amdgcn_mfma_f32_16x16x32_bf16(Bt[n][k], At[m][k], acc[ai][bj][m][n], 0, 0, 0); __builtin_amdgcn_s_setprio(0); } while (0)
; #define PG8_WAIT_V(n) asm volatile("s_waitcnt vmcnt(" #n ")" ::: "memory")
; #define PG8_WAIT_L(n) asm volatile("s_waitcnt lgkmcnt(" #n ")" ::: "memory")
; #define PG8_BAR __builtin_amdgcn_s_barrier()
; #define PG8_SCHED __builtin_amdgcn_sched_barrier(0)
; template <class Epi>
; DI void gemm_phase(LAS unsigned char* lds, const Gemm g, const Order& S, const Epi& E, const int wv) {
;     ...
;             PG8_WAIT_V(8); PG8_WAIT_L(0); PG8_BAR; PG8_MMA(1, 0, At, B0); PG8_MMA(1, 1, At, B1); PG8_BAR; PG8_SCHED;
;             PG8_LDB(B0, 1, 0); PG8_LDB(B1, 1, 1); PG8_SCHED; PG8_LDA(At, 1, 0); PG8_STAGE(PG8_SA(0, 1), a2 + hstep, voffA);
;             PG8_WAIT_V(8); PG8_WAIT_L(0); PG8_BAR; PG8_MMA(0, 0, At, B0); PG8_MMA(0, 1, At, B1); PG8_BAR; PG8_SCHED;
	s_waitcnt lgkmcnt(0)
	v_mfma_f32_16x16x32_bf16 v[60:63], v[144:147], v[180:183], v[60:63]
	v_mfma_f32_16x16x32_bf16 v[56:59], v[156:159], v[180:183], v[56:59]
	v_mfma_f32_16x16x32_bf16 v[44:47], v[144:147], v[192:195], v[44:47]
	v_mfma_f32_16x16x32_bf16 v[40:43], v[156:159], v[192:195], v[40:43]
	v_mfma_f32_16x16x32_bf16 v[28:31], v[144:147], v[204:207], v[28:31]
	v_mfma_f32_16x16x32_bf16 v[24:27], v[156:159], v[204:207], v[24:27]
	v_mfma_f32_16x16x32_bf16 v[12:15], v[144:147], v[212:215], v[12:15]
	v_mfma_f32_16x16x32_bf16 v[8:11], v[156:159], v[212:215], v[8:11]
	v_mfma_f32_16x16x32_bf16 v[60:63], v[152:155], v[184:187], v[60:63]
	v_mfma_f32_16x16x32_bf16 v[56:59], v[160:163], v[184:187], v[56:59]
	v_mfma_f32_16x16x32_bf16 v[44:47], v[152:155], v[196:199], v[44:47]
	v_mfma_f32_16x16x32_bf16 v[40:43], v[160:163], v[196:199], v[40:43]
	v_mfma_f32_16x16x32_bf16 v[28:31], v[152:155], v[208:211], v[28:31]
	v_mfma_f32_16x16x32_bf16 v[24:27], v[160:163], v[208:211], v[24:27]
	v_mfma_f32_16x16x32_bf16 v[12:15], v[152:155], v[216:219], v[12:15]
	v_mfma_f32_16x16x32_bf16 v[8:11], v[160:163], v[216:219], v[8:11]
	v_mfma_f32_16x16x32_bf16 v[52:55], v[164:167], v[180:183], v[52:55]
	v_mfma_f32_16x16x32_bf16 v[48:51], v[172:175], v[180:183], v[48:51]
	v_mfma_f32_16x16x32_bf16 v[36:39], v[164:167], v[192:195], v[36:39]
	v_mfma_f32_16x16x32_bf16 v[32:35], v[172:175], v[192:195], v[32:35]
	v_mfma_f32_16x16x32_bf16 v[20:23], v[164:167], v[204:207], v[20:23]
	v_mfma_f32_16x16x32_bf16 v[16:19], v[172:175], v[204:207], v[16:19]
	v_mfma_f32_16x16x32_bf16 v[4:7], v[164:167], v[212:215], v[4:7]
	v_mfma_f32_16x16x32_bf16 v[0:3], v[172:175], v[212:215], v[0:3]
	v_mfma_f32_16x16x32_bf16 v[52:55], v[168:171], v[184:187], v[52:55]
	v_mfma_f32_16x16x32_bf16 v[48:51], v[176:179], v[184:187], v[48:51]
	v_mfma_f32_16x16x32_bf16 v[36:39], v[168:171], v[196:199], v[36:39]
	v_mfma_f32_16x16x32_bf16 v[32:35], v[176:179], v[196:199], v[32:35]
	v_mfma_f32_16x16x32_bf16 v[20:23], v[168:171], v[208:211], v[20:23]
	v_mfma_f32_16x16x32_bf16 v[16:19], v[176:179], v[208:211], v[16:19]
	v_mfma_f32_16x16x32_bf16 v[4:7], v[168:171], v[216:219], v[4:7]
	v_mfma_f32_16x16x32_bf16 v[0:3], v[176:179], v[216:219], v[0:3]
	s_barrier
	s_add_i32 s43, 0, 0x18000
	v_add_u32_e32 v149, s43, v141
	s_add_i32 s44, 0, 0x1c000
	ds_read_b128 v[144:147], v149
	ds_read_b128 v[152:155], v149 offset:1024
	ds_read_b128 v[156:159], v149 offset:2048
	ds_read_b128 v[160:163], v149 offset:3072
	v_add_u32_e32 v149, s44, v141
	ds_read_b128 v[164:167], v149
	ds_read_b128 v[168:171], v149 offset:1024
	ds_read_b128 v[172:175], v149 offset:2048
	ds_read_b128 v[176:179], v149 offset:3072
	s_add_u32 s20, s20, 0x40000
	s_addc_u32 s21, s21, 0
	s_mov_b32 m0, s29
	v_lshl_add_u64 v[226:227], s[20:21], 0, v[130:131]
	ds_read_b128 v[180:183], v143 offset:32768
	ds_read_b128 v[184:187], v143 offset:33792
	ds_read_b128 v[192:195], v143 offset:34816
	ds_read_b128 v[196:199], v143 offset:35840
	ds_read_b128 v[204:207], v143 offset:36864
	ds_read_b128 v[208:211], v143 offset:37888
	ds_read_b128 v[212:215], v143 offset:38912
	ds_read_b128 v[216:219], v143 offset:39936
	global_load_lds_dwordx4 v[226:227], off
	v_lshl_add_u64 v[226:227], s[20:21], 0, v[132:133]
	s_mov_b32 m0, s30
	s_nop 0
	global_load_lds_dwordx4 v[226:227], off
	s_waitcnt vmcnt(8)
	s_waitcnt lgkmcnt(0)
	s_barrier
	s_waitcnt lgkmcnt(0)
	v_mfma_f32_16x16x32_bf16 v[126:129], v[144:147], v[180:183], v[126:129]
	v_mfma_f32_16x16x32_bf16 v[122:125], v[156:159], v[180:183], v[122:125]
	v_mfma_f32_16x16x32_bf16 v[108:111], v[144:147], v[192:195], v[108:111]
	v_mfma_f32_16x16x32_bf16 v[104:107], v[156:159], v[192:195], v[104:107]
	v_mfma_f32_16x16x32_bf16 v[92:95], v[144:147], v[204:207], v[92:95]
	v_mfma_f32_16x16x32_bf16 v[88:91], v[156:159], v[204:207], v[88:91]
	v_mfma_f32_16x16x32_bf16 v[76:79], v[144:147], v[212:215], v[76:79]
	v_mfma_f32_16x16x32_bf16 v[72:75], v[156:159], v[212:215], v[72:75]
	v_mfma_f32_16x16x32_bf16 v[126:129], v[152:155], v[184:187], v[126:129]
	v_mfma_f32_16x16x32_bf16 v[122:125], v[160:163], v[184:187], v[122:125]
	v_mfma_f32_16x16x32_bf16 v[108:111], v[152:155], v[196:199], v[108:111]
	v_mfma_f32_16x16x32_bf16 v[104:107], v[160:163], v[196:199], v[104:107]
	v_mfma_f32_16x16x32_bf16 v[92:95], v[152:155], v[208:211], v[92:95]
	v_mfma_f32_16x16x32_bf16 v[88:91], v[160:163], v[208:211], v[88:91]
	v_mfma_f32_16x16x32_bf16 v[76:79], v[152:155], v[216:219], v[76:79]
	v_mfma_f32_16x16x32_bf16 v[72:75], v[160:163], v[216:219], v[72:75]
	v_mfma_f32_16x16x32_bf16 v[118:121], v[164:167], v[180:183], v[118:121]
	v_mfma_f32_16x16x32_bf16 v[114:117], v[172:175], v[180:183], v[114:117]
	v_mfma_f32_16x16x32_bf16 v[100:103], v[164:167], v[192:195], v[100:103]
	v_mfma_f32_16x16x32_bf16 v[96:99], v[172:175], v[192:195], v[96:99]
	v_mfma_f32_16x16x32_bf16 v[84:87], v[164:167], v[204:207], v[84:87]
	v_mfma_f32_16x16x32_bf16 v[80:83], v[172:175], v[204:207], v[80:83]
	v_mfma_f32_16x16x32_bf16 v[68:71], v[164:167], v[212:215], v[68:71]
	v_mfma_f32_16x16x32_bf16 v[64:67], v[172:175], v[212:215], v[64:67]
	v_mfma_f32_16x16x32_bf16 v[118:121], v[168:171], v[184:187], v[118:121]
	v_mfma_f32_16x16x32_bf16 v[114:117], v[176:179], v[184:187], v[114:117]
	v_mfma_f32_16x16x32_bf16 v[100:103], v[168:171], v[196:199], v[100:103]
	v_mfma_f32_16x16x32_bf16 v[96:99], v[176:179], v[196:199], v[96:99]
	v_mfma_f32_16x16x32_bf16 v[84:87], v[168:171], v[208:211], v[84:87]
	v_mfma_f32_16x16x32_bf16 v[80:83], v[176:179], v[208:211], v[80:83]
	v_mfma_f32_16x16x32_bf16 v[68:71], v[168:171], v[216:219], v[68:71]
	v_mfma_f32_16x16x32_bf16 v[64:67], v[176:179], v[216:219], v[64:67]
	s_barrier
; #define PG8_STAGE(bufoff, gbase, voff) do { _Pragma("unroll") for (int _i = 0; _i < 2; ++_i) \
;         __builtin_amdgcn_global_load_lds((const unsigned*)((const char*)(gbase) + (voff)[_i]), (LAS unsigned*)(lds + (bufoff) + ldsw + _i * 8192), 16, 0, 0); } while (0)
; #define PG8_LDA(dst, b, h) do { _Pragma("unroll") for (int m = 0; m < 4; ++m) _Pragma("unroll") for (int k = 0; k < 2; ++k) dst[m][k] = *(const LAS bf16x8*)(lds + PG8_SA(b, h) + aoff + m * 2048 + k * 1024); } while (0)
; #define PG8_MMA(ai, bj, At, Bt) do { __builtin_amdgcn_s_setprio(1); _Pragma("unroll") for (int m = 0; m < 4; ++m) _Pragma("unroll") for (int n = 0; n < 2; ++n) _Pragma("unroll") for (int k = 0; k < 2; ++k) \
;         acc[ai][bj][m][n] = __builtin_amdgcn_mfma_f32_16x16x32_bf16(Bt[n][k], At[m][k], acc[ai][bj][m][n], 0, 0, 0); __builtin_amdgcn_s_setprio(0); } while (0)
; #define PG8_WAIT_V(n) asm volatile("s_waitcnt vmcnt(" #n ")" ::: "memory")
; #define PG8_WAIT_L(n) asm volatile("s_waitcnt lgkmcnt(" #n ")" ::: "memory")
; #define PG8_BAR __builtin_amdgcn_s_barrier()
; #define PG8_SCHED __builtin_amdgcn_sched_barrier(0)
; template <class Epi>
; DI void gemm_phase(LAS unsigned char* lds, const Gemm g, const Order& S, const Epi& E, const int wv) {
;     ...
;             PG8_LDA(At, 1, 1); PG8_STAGE(PG8_SB(1, 0), b3, voffB); PG8_STAGE(PG8_SB(1, 1), b3 + hstep, voffB); PG8_STAGE(PG8_SA(1, 0), a3, voffA);
;             PG8_WAIT_V(8); PG8_WAIT_L(0); PG8_BAR; PG8_MMA(1, 0, At, B0); PG8_MMA(1, 1, At, B1); PG8_BAR; PG8_SCHED;
;         }
;         if (wr == 0) PG8_BAR;
	s_add_i32 s20, s43, s47
	v_lshl_add_u64 v[188:189], v[188:189], 0, s[48:49]
	s_mov_b32 m0, s20
	ds_read_b128 v[180:183], v143 offset:49152
	ds_read_b128 v[184:187], v143 offset:50176
	ds_read_b128 v[192:195], v143 offset:51200
	ds_read_b128 v[196:199], v143 offset:52224
	ds_read_b128 v[204:207], v143 offset:53248
	ds_read_b128 v[208:211], v143 offset:54272
	ds_read_b128 v[212:215], v143 offset:55296
	ds_read_b128 v[216:219], v143 offset:56320
	global_load_lds_dwordx4 v[188:189], off
	s_add_i32 m0, s20, 0x2000
	s_add_u32 s18, s18, 0x40080
	v_lshl_add_u64 v[188:189], v[220:221], 0, s[48:49]
	s_addc_u32 s19, s19, 0
	s_add_i32 s20, s44, s47
	global_load_lds_dwordx4 v[188:189], off
	v_lshl_add_u64 v[188:189], s[18:19], 0, v[112:113]
	s_mov_b32 m0, s20
	s_nop 0
	global_load_lds_dwordx4 v[188:189], off
	v_lshl_add_u64 v[188:189], s[18:19], 0, v[134:135]
	s_add_i32 m0, s20, 0x2000
	s_nop 0
	global_load_lds_dwordx4 v[188:189], off
	v_lshl_add_u64 v[188:189], v[222:223], 0, s[48:49]
	s_mov_b32 m0, s31
	s_nop 0
	global_load_lds_dwordx4 v[188:189], off
	v_lshl_add_u64 v[188:189], v[224:225], 0, s[48:49]
	s_mov_b32 m0, s33
	s_nop 0
	global_load_lds_dwordx4 v[188:189], off
	s_waitcnt vmcnt(8)
	s_waitcnt lgkmcnt(0)
	s_barrier
	s_waitcnt lgkmcnt(0)
	v_mfma_f32_16x16x32_bf16 v[60:63], v[144:147], v[180:183], v[60:63]
	v_mfma_f32_16x16x32_bf16 v[56:59], v[156:159], v[180:183], v[56:59]
	v_mfma_f32_16x16x32_bf16 v[44:47], v[144:147], v[192:195], v[44:47]
	v_mfma_f32_16x16x32_bf16 v[40:43], v[156:159], v[192:195], v[40:43]
	v_mfma_f32_16x16x32_bf16 v[28:31], v[144:147], v[204:207], v[28:31]
	v_mfma_f32_16x16x32_bf16 v[24:27], v[156:159], v[204:207], v[24:27]
	v_mfma_f32_16x16x32_bf16 v[12:15], v[144:147], v[212:215], v[12:15]
	v_mfma_f32_16x16x32_bf16 v[8:11], v[156:159], v[212:215], v[8:11]
	v_mfma_f32_16x16x32_bf16 v[60:63], v[152:155], v[184:187], v[60:63]
	v_mfma_f32_16x16x32_bf16 v[56:59], v[160:163], v[184:187], v[56:59]
	v_mfma_f32_16x16x32_bf16 v[44:47], v[152:155], v[196:199], v[44:47]
	v_mfma_f32_16x16x32_bf16 v[40:43], v[160:163], v[196:199], v[40:43]
	v_mfma_f32_16x16x32_bf16 v[28:31], v[152:155], v[208:211], v[28:31]
	v_mfma_f32_16x16x32_bf16 v[24:27], v[160:163], v[208:211], v[24:27]
	v_mfma_f32_16x16x32_bf16 v[12:15], v[152:155], v[216:219], v[12:15]
	v_mfma_f32_16x16x32_bf16 v[8:11], v[160:163], v[216:219], v[8:11]
	v_mfma_f32_16x16x32_bf16 v[52:55], v[164:167], v[180:183], v[52:55]
	v_mfma_f32_16x16x32_bf16 v[48:51], v[172:175], v[180:183], v[48:51]
	v_mfma_f32_16x16x32_bf16 v[36:39], v[164:167], v[192:195], v[36:39]
	v_mfma_f32_16x16x32_bf16 v[32:35], v[172:175], v[192:195], v[32:35]
	v_mfma_f32_16x16x32_bf16 v[20:23], v[164:167], v[204:207], v[20:23]
	v_mfma_f32_16x16x32_bf16 v[16:19], v[172:175], v[204:207], v[16:19]
	v_mfma_f32_16x16x32_bf16 v[4:7], v[164:167], v[212:215], v[4:7]
	v_mfma_f32_16x16x32_bf16 v[0:3], v[172:175], v[212:215], v[0:3]
	v_mfma_f32_16x16x32_bf16 v[52:55], v[168:171], v[184:187], v[52:55]
	v_mfma_f32_16x16x32_bf16 v[48:51], v[176:179], v[184:187], v[48:51]
	v_mfma_f32_16x16x32_bf16 v[36:39], v[168:171], v[196:199], v[36:39]
	v_mfma_f32_16x16x32_bf16 v[32:35], v[176:179], v[196:199], v[32:35]
	v_mfma_f32_16x16x32_bf16 v[20:23], v[168:171], v[208:211], v[20:23]
	v_mfma_f32_16x16x32_bf16 v[16:19], v[176:179], v[208:211], v[16:19]
	v_mfma_f32_16x16x32_bf16 v[4:7], v[168:171], v[216:219], v[4:7]
	v_mfma_f32_16x16x32_bf16 v[0:3], v[176:179], v[216:219], v[0:3]
	s_barrier
	s_add_i32 s42, s42, 2
	s_add_u32 s16, s16, 0x100
	s_addc_u32 s17, s17, 0
	s_add_u32 s40, s40, 0x100
	s_addc_u32 s41, s41, 0
	s_cmp_gt_u32 s42, 13
	s_cbranch_scc0 .LBB0_908
	v_readlane_b32 s16, v253, 24
	v_readlane_b32 s17, v253, 25
	s_and_b64 vcc, exec, s[16:17]
	s_cbranch_vccz .LBB0_911
	s_barrier

; #define PG8_STAGE(bufoff, gbase, voff) do { _Pragma("unroll") for (int _i = 0; _i < 2; ++_i) \
;         __builtin_amdgcn_global_load_lds((const unsigned*)((const char*)(gbase) + (voff)[_i]), (LAS unsigned*)(lds + (bufoff) + ldsw + _i * 8192), 16, 0, 0); } while (0)
; #define PG8_LDA(dst, b, h) do { _Pragma("unroll") for (int m = 0; m < 4; ++m) _Pragma("unroll") for (int k = 0; k < 2; ++k) dst[m][k] = *(const LAS bf16x8*)(lds + PG8_SA(b, h) + aoff + m * 2048 + k * 1024); } while (0)
; #define PG8_LDB(dst, b, h) do { _Pragma("unroll") for (int n = 0; n < 2; ++n) _Pragma("unroll") for (int k = 0; k < 2; ++k) dst[n][k] = *(const LAS bf16x8*)(lds + PG8_SB(b, h) + boff + n * 2048 + k * 1024); } while (0)
; #define PG8_MMA(ai, bj, At, Bt) do { __builtin_amdgcn_s_setprio(1); _Pragma("unroll") for (int m = 0; m < 4; ++m) _Pragma("unroll") for (int n = 0; n < 2; ++n) _Pragma("unroll") for (int k = 0; k < 2; ++k) \
;         acc[ai][bj][m][n] = __builtin_amdgcn_mfma_f32_16x16x32_bf16(Bt[n][k], At[m][k], acc[ai][bj][m][n], 0, 0, 0); __builtin_amdgcn_s_setprio(0); } while (0)
; #define PG8_WAIT_V(n) asm volatile("s_waitcnt vmcnt(" #n ")" ::: "memory")
; #define PG8_WAIT_L(n) asm volatile("s_waitcnt lgkmcnt(" #n ")" ::: "memory")
; #define PG8_BAR __builtin_amdgcn_s_barrier()
; #define PG8_SCHED __builtin_amdgcn_sched_barrier(0)
; template <class Epi>
; DI void gemm_phase(LAS unsigned char* lds, const Gemm g, const Order& S, const Epi& E, const int wv) {
;     ...
;         for (int t = 0; t < nt; t += 2) {
;             const bool last = (t == nt - 2);
;             const char* a1 = cA + (size_t)(t + 1) * kstep;
;             const char* a2 = last ? nA : cA + (size_t)(t + 2) * kstep; const char* b2 = last ? nB : cB + (size_t)(t + 2) * kstep;
;             const char* a3 = a2 + kstep; const char* b3 = b2 + kstep;
;             PG8_LDB(B0, 0, 0); PG8_LDB(B1, 0, 1); PG8_SCHED; PG8_LDA(At, 0, 0); PG8_STAGE(PG8_SA(1, 1), a1 + hstep, voffA);
;             PG8_WAIT_V(8); PG8_WAIT_L(0); PG8_BAR; PG8_MMA(0, 0, At, B0); PG8_MMA(0, 1, At, B1); PG8_BAR; PG8_SCHED;
;             PG8_LDA(At, 0, 1); PG8_STAGE(PG8_SB(0, 0), b2, voffB); PG8_STAGE(PG8_SB(0, 1), b2 + hstep, voffB); PG8_STAGE(PG8_SA(0, 0), a2, voffA);
;             PG8_WAIT_V(8); PG8_WAIT_L(0); PG8_BAR; PG8_MMA(1, 0, At, B0); PG8_MMA(1, 1, At, B1); PG8_BAR; PG8_SCHED;
.LBB0_989:
	s_add_i32 s26, s18, 2
	s_add_u32 s19, s16, 0xfff00080
	s_addc_u32 s20, s17, -1
	s_add_i32 s27, 0, 0x10000
	s_cmp_eq_u32 s23, s18
	s_cselect_b32 s21, s1, s20
	s_cselect_b32 s20, s7, s19
	v_add_u32_e32 v149, s27, v150
	s_cselect_b32 s19, s5, s25
	s_cselect_b32 s18, s15, s24
	s_add_i32 s47, 0, 0x14000
	ds_read_b128 v[130:133], v149
	ds_read_b128 v[134:137], v149 offset:1024
	ds_read_b128 v[138:141], v149 offset:2048
	ds_read_b128 v[174:177], v149 offset:3072
	v_add_u32_e32 v149, s47, v150
	ds_read_b128 v[178:181], v149
	ds_read_b128 v[182:185], v149 offset:1024
	ds_read_b128 v[186:189], v149 offset:2048
	ds_read_b128 v[192:195], v149 offset:3072
	v_lshl_add_u64 v[152:153], s[16:17], 0, v[170:171]
	s_add_i32 m0, s30, 0xc000
	ds_read_b128 v[196:199], v205
	ds_read_b128 v[206:209], v205 offset:1024
	ds_read_b128 v[210:213], v205 offset:2048
	ds_read_b128 v[214:217], v205 offset:3072
	ds_read_b128 v[218:221], v205 offset:4096
	ds_read_b128 v[222:225], v205 offset:5120
	ds_read_b128 v[226:229], v205 offset:6144
	ds_read_b128 v[230:233], v205 offset:7168
	global_load_lds_dwordx4 v[152:153], off
	v_lshl_add_u64 v[152:153], s[16:17], 0, v[172:173]
	s_add_i32 m0, s30, 0xe000
	s_nop 0
	global_load_lds_dwordx4 v[152:153], off
	s_waitcnt vmcnt(8)
	s_waitcnt lgkmcnt(0)
	s_barrier
	s_waitcnt lgkmcnt(0)
	v_mfma_f32_16x16x32_bf16 v[126:129], v[130:133], v[196:199], v[126:129]
	v_mfma_f32_16x16x32_bf16 v[122:125], v[138:141], v[196:199], v[122:125]
	v_mfma_f32_16x16x32_bf16 v[118:121], v[130:133], v[210:213], v[118:121]
	v_mfma_f32_16x16x32_bf16 v[114:117], v[138:141], v[210:213], v[114:117]
	v_mfma_f32_16x16x32_bf16 v[108:111], v[130:133], v[218:221], v[108:111]
	v_mfma_f32_16x16x32_bf16 v[104:107], v[138:141], v[218:221], v[104:107]
	v_mfma_f32_16x16x32_bf16 v[100:103], v[130:133], v[226:229], v[100:103]
	v_mfma_f32_16x16x32_bf16 v[96:99], v[138:141], v[226:229], v[96:99]
	v_mfma_f32_16x16x32_bf16 v[126:129], v[134:137], v[206:209], v[126:129]
	v_mfma_f32_16x16x32_bf16 v[122:125], v[174:177], v[206:209], v[122:125]
	v_mfma_f32_16x16x32_bf16 v[118:121], v[134:137], v[214:217], v[118:121]
	v_mfma_f32_16x16x32_bf16 v[114:117], v[174:177], v[214:217], v[114:117]
	v_mfma_f32_16x16x32_bf16 v[108:111], v[134:137], v[222:225], v[108:111]
	v_mfma_f32_16x16x32_bf16 v[104:107], v[174:177], v[222:225], v[104:107]
	v_mfma_f32_16x16x32_bf16 v[100:103], v[134:137], v[230:233], v[100:103]
	v_mfma_f32_16x16x32_bf16 v[96:99], v[174:177], v[230:233], v[96:99]
	v_mfma_f32_16x16x32_bf16 v[60:63], v[178:181], v[196:199], v[60:63]
	v_mfma_f32_16x16x32_bf16 v[56:59], v[186:189], v[196:199], v[56:59]
	v_mfma_f32_16x16x32_bf16 v[52:55], v[178:181], v[210:213], v[52:55]
	v_mfma_f32_16x16x32_bf16 v[48:51], v[186:189], v[210:213], v[48:51]
	v_mfma_f32_16x16x32_bf16 v[44:47], v[178:181], v[218:221], v[44:47]
	v_mfma_f32_16x16x32_bf16 v[40:43], v[186:189], v[218:221], v[40:43]
	v_mfma_f32_16x16x32_bf16 v[36:39], v[178:181], v[226:229], v[36:39]
	v_mfma_f32_16x16x32_bf16 v[32:35], v[186:189], v[226:229], v[32:35]
	v_mfma_f32_16x16x32_bf16 v[60:63], v[182:185], v[206:209], v[60:63]
	v_mfma_f32_16x16x32_bf16 v[56:59], v[192:195], v[206:209], v[56:59]
	v_mfma_f32_16x16x32_bf16 v[52:55], v[182:185], v[214:217], v[52:55]
	v_mfma_f32_16x16x32_bf16 v[48:51], v[192:195], v[214:217], v[48:51]
	v_mfma_f32_16x16x32_bf16 v[44:47], v[182:185], v[222:225], v[44:47]
	v_mfma_f32_16x16x32_bf16 v[40:43], v[192:195], v[222:225], v[40:43]
	v_mfma_f32_16x16x32_bf16 v[36:39], v[182:185], v[230:233], v[36:39]
	v_mfma_f32_16x16x32_bf16 v[32:35], v[192:195], v[230:233], v[32:35]
	s_barrier
	s_add_i32 s27, s27, s50
	v_lshl_add_u64 v[152:153], s[18:19], 0, v[112:113]
	s_mov_b32 m0, s27
	ds_read_b128 v[196:199], v205 offset:16384
	ds_read_b128 v[206:209], v205 offset:17408
	ds_read_b128 v[210:213], v205 offset:18432
	ds_read_b128 v[214:217], v205 offset:19456
	ds_read_b128 v[218:221], v205 offset:20480
	ds_read_b128 v[222:225], v205 offset:21504
	ds_read_b128 v[226:229], v205 offset:22528
	ds_read_b128 v[230:233], v205 offset:23552
	global_load_lds_dwordx4 v[152:153], off
	s_add_i32 m0, s27, 0x2000
	s_add_u32 s48, s18, 0x100000
	v_lshl_add_u64 v[234:235], s[18:19], 0, v[146:147]
	s_addc_u32 s49, s19, 0
	s_add_i32 s27, s47, s50
	global_load_lds_dwordx4 v[234:235], off
	v_lshl_add_u64 v[236:237], s[48:49], 0, v[112:113]
	s_mov_b32 m0, s27
	v_lshl_add_u64 v[238:239], s[20:21], 0, v[144:145]
	global_load_lds_dwordx4 v[236:237], off
	v_lshl_add_u64 v[236:237], s[48:49], 0, v[146:147]
	s_add_i32 m0, s27, 0x2000
	s_nop 0
	global_load_lds_dwordx4 v[236:237], off
	v_lshl_add_u64 v[236:237], s[20:21], 0, v[142:143]
	s_mov_b32 m0, s30
	s_nop 0
	global_load_lds_dwordx4 v[236:237], off
	s_mov_b32 m0, s31
	s_nop 0
	global_load_lds_dwordx4 v[238:239], off
	s_waitcnt vmcnt(8)
	s_waitcnt lgkmcnt(0)
	s_barrier
; #define PG8_STAGE(bufoff, gbase, voff) do { _Pragma("unroll") for (int _i = 0; _i < 2; ++_i) \
;         __builtin_amdgcn_global_load_lds((const unsigned*)((const char*)(gbase) + (voff)[_i]), (LAS unsigned*)(lds + (bufoff) + ldsw + _i * 8192), 16, 0, 0); } while (0)
; #define PG8_LDA(dst, b, h) do { _Pragma("unroll") for (int m = 0; m < 4; ++m) _Pragma("unroll") for (int k = 0; k < 2; ++k) dst[m][k] = *(const LAS bf16x8*)(lds + PG8_SA(b, h) + aoff + m * 2048 + k * 1024); } while (0)
; #define PG8_LDB(dst, b, h) do { _Pragma("unroll") for (int n = 0; n < 2; ++n) _Pragma("unroll") for (int k = 0; k < 2; ++k) dst[n][k] = *(const LAS bf16x8*)(lds + PG8_SB(b, h) + boff + n * 2048 + k * 1024); } while (0)
; #define PG8_MMA(ai, bj, At, Bt) do { __builtin_amdgcn_s_setprio(1); _Pragma("unroll") for (int m = 0; m < 4; ++m) _Pragma("unroll") for (int n = 0; n < 2; ++n) _Pragma("unroll") for (int k = 0; k < 2; ++k) \
;         acc[ai][bj][m][n] = __builtin_amdgcn_mfma_f32_16x16x32_bf16(Bt[n][k], At[m][k], acc[ai][bj][m][n], 0, 0, 0); __builtin_amdgcn_s_setprio(0); } while (0)
; #define PG8_WAIT_V(n) asm volatile("s_waitcnt vmcnt(" #n ")" ::: "memory")
; #define PG8_WAIT_L(n) asm volatile("s_waitcnt lgkmcnt(" #n ")" ::: "memory")
; #define PG8_BAR __builtin_amdgcn_s_barrier()
; #define PG8_SCHED __builtin_amdgcn_sched_barrier(0)
; template <class Epi>
; DI void gemm_phase(LAS unsigned char* lds, const Gemm g, const Order& S, const Epi& E, const int wv) {
;     ...
;             PG8_WAIT_V(8); PG8_WAIT_L(0); PG8_BAR; PG8_MMA(1, 0, At, B0); PG8_MMA(1, 1, At, B1); PG8_BAR; PG8_SCHED;
;             PG8_LDB(B0, 1, 0); PG8_LDB(B1, 1, 1); PG8_SCHED; PG8_LDA(At, 1, 0); PG8_STAGE(PG8_SA(0, 1), a2 + hstep, voffA);
;             PG8_WAIT_V(8); PG8_WAIT_L(0); PG8_BAR; PG8_MMA(0, 0, At, B0); PG8_MMA(0, 1, At, B1); PG8_BAR; PG8_SCHED;
	s_waitcnt lgkmcnt(0)
	v_mfma_f32_16x16x32_bf16 v[92:95], v[130:133], v[196:199], v[92:95]
	v_mfma_f32_16x16x32_bf16 v[88:91], v[138:141], v[196:199], v[88:91]
	v_mfma_f32_16x16x32_bf16 v[84:87], v[130:133], v[210:213], v[84:87]
	v_mfma_f32_16x16x32_bf16 v[80:83], v[138:141], v[210:213], v[80:83]
	v_mfma_f32_16x16x32_bf16 v[76:79], v[130:133], v[218:221], v[76:79]
	v_mfma_f32_16x16x32_bf16 v[72:75], v[138:141], v[218:221], v[72:75]
	v_mfma_f32_16x16x32_bf16 v[68:71], v[130:133], v[226:229], v[68:71]
	v_mfma_f32_16x16x32_bf16 v[64:67], v[138:141], v[226:229], v[64:67]
	v_mfma_f32_16x16x32_bf16 v[92:95], v[134:137], v[206:209], v[92:95]
	v_mfma_f32_16x16x32_bf16 v[88:91], v[174:177], v[206:209], v[88:91]
	v_mfma_f32_16x16x32_bf16 v[84:87], v[134:137], v[214:217], v[84:87]
	v_mfma_f32_16x16x32_bf16 v[80:83], v[174:177], v[214:217], v[80:83]
	v_mfma_f32_16x16x32_bf16 v[76:79], v[134:137], v[222:225], v[76:79]
	v_mfma_f32_16x16x32_bf16 v[72:75], v[174:177], v[222:225], v[72:75]
	v_mfma_f32_16x16x32_bf16 v[68:71], v[134:137], v[230:233], v[68:71]
	v_mfma_f32_16x16x32_bf16 v[64:67], v[174:177], v[230:233], v[64:67]
	v_mfma_f32_16x16x32_bf16 v[28:31], v[178:181], v[196:199], v[28:31]
	v_mfma_f32_16x16x32_bf16 v[24:27], v[186:189], v[196:199], v[24:27]
	v_mfma_f32_16x16x32_bf16 v[20:23], v[178:181], v[210:213], v[20:23]
	v_mfma_f32_16x16x32_bf16 v[16:19], v[186:189], v[210:213], v[16:19]
	v_mfma_f32_16x16x32_bf16 v[12:15], v[178:181], v[218:221], v[12:15]
	v_mfma_f32_16x16x32_bf16 v[8:11], v[186:189], v[218:221], v[8:11]
	v_mfma_f32_16x16x32_bf16 v[4:7], v[178:181], v[226:229], v[4:7]
	v_mfma_f32_16x16x32_bf16 v[0:3], v[186:189], v[226:229], v[0:3]
	v_mfma_f32_16x16x32_bf16 v[28:31], v[182:185], v[206:209], v[28:31]
	v_mfma_f32_16x16x32_bf16 v[24:27], v[192:195], v[206:209], v[24:27]
	v_mfma_f32_16x16x32_bf16 v[20:23], v[182:185], v[214:217], v[20:23]
	v_mfma_f32_16x16x32_bf16 v[16:19], v[192:195], v[214:217], v[16:19]
	v_mfma_f32_16x16x32_bf16 v[12:15], v[182:185], v[222:225], v[12:15]
	v_mfma_f32_16x16x32_bf16 v[8:11], v[192:195], v[222:225], v[8:11]
	v_mfma_f32_16x16x32_bf16 v[4:7], v[182:185], v[230:233], v[4:7]
	v_mfma_f32_16x16x32_bf16 v[0:3], v[192:195], v[230:233], v[0:3]
	s_barrier
	s_add_i32 s27, 0, 0x18000
	v_add_u32_e32 v149, s27, v150
	s_add_i32 s47, 0, 0x1c000
	ds_read_b128 v[130:133], v149
	ds_read_b128 v[134:137], v149 offset:1024
	ds_read_b128 v[138:141], v149 offset:2048
	ds_read_b128 v[174:177], v149 offset:3072
	v_add_u32_e32 v149, s47, v150
	ds_read_b128 v[178:181], v149
	ds_read_b128 v[182:185], v149 offset:1024
	ds_read_b128 v[186:189], v149 offset:2048
	ds_read_b128 v[192:195], v149 offset:3072
	s_add_u32 s20, s20, 0x100000
	s_addc_u32 s21, s21, 0
	s_mov_b32 m0, s33
	v_lshl_add_u64 v[240:241], s[20:21], 0, v[142:143]
	ds_read_b128 v[196:199], v205 offset:32768
	ds_read_b128 v[206:209], v205 offset:33792
	ds_read_b128 v[210:213], v205 offset:34816
	ds_read_b128 v[214:217], v205 offset:35840
	ds_read_b128 v[218:221], v205 offset:36864
	ds_read_b128 v[222:225], v205 offset:37888
	ds_read_b128 v[226:229], v205 offset:38912
	ds_read_b128 v[230:233], v205 offset:39936
	global_load_lds_dwordx4 v[240:241], off
	v_lshl_add_u64 v[240:241], s[20:21], 0, v[144:145]
	s_mov_b32 m0, s34
	s_nop 0
	global_load_lds_dwordx4 v[240:241], off
	s_waitcnt vmcnt(8)
	s_waitcnt lgkmcnt(0)
	s_barrier
	s_waitcnt lgkmcnt(0)
	v_mfma_f32_16x16x32_bf16 v[126:129], v[130:133], v[196:199], v[126:129]
	v_mfma_f32_16x16x32_bf16 v[122:125], v[138:141], v[196:199], v[122:125]
	v_mfma_f32_16x16x32_bf16 v[118:121], v[130:133], v[210:213], v[118:121]
	v_mfma_f32_16x16x32_bf16 v[114:117], v[138:141], v[210:213], v[114:117]
	v_mfma_f32_16x16x32_bf16 v[108:111], v[130:133], v[218:221], v[108:111]
	v_mfma_f32_16x16x32_bf16 v[104:107], v[138:141], v[218:221], v[104:107]
	v_mfma_f32_16x16x32_bf16 v[100:103], v[130:133], v[226:229], v[100:103]
	v_mfma_f32_16x16x32_bf16 v[96:99], v[138:141], v[226:229], v[96:99]
	v_mfma_f32_16x16x32_bf16 v[126:129], v[134:137], v[206:209], v[126:129]
	v_mfma_f32_16x16x32_bf16 v[122:125], v[174:177], v[206:209], v[122:125]
	v_mfma_f32_16x16x32_bf16 v[118:121], v[134:137], v[214:217], v[118:121]
	v_mfma_f32_16x16x32_bf16 v[114:117], v[174:177], v[214:217], v[114:117]
	v_mfma_f32_16x16x32_bf16 v[108:111], v[134:137], v[222:225], v[108:111]
	v_mfma_f32_16x16x32_bf16 v[104:107], v[174:177], v[222:225], v[104:107]
	v_mfma_f32_16x16x32_bf16 v[100:103], v[134:137], v[230:233], v[100:103]
	v_mfma_f32_16x16x32_bf16 v[96:99], v[174:177], v[230:233], v[96:99]
	v_mfma_f32_16x16x32_bf16 v[60:63], v[178:181], v[196:199], v[60:63]
	v_mfma_f32_16x16x32_bf16 v[56:59], v[186:189], v[196:199], v[56:59]
	v_mfma_f32_16x16x32_bf16 v[52:55], v[178:181], v[210:213], v[52:55]
	v_mfma_f32_16x16x32_bf16 v[48:51], v[186:189], v[210:213], v[48:51]
	v_mfma_f32_16x16x32_bf16 v[44:47], v[178:181], v[218:221], v[44:47]
	v_mfma_f32_16x16x32_bf16 v[40:43], v[186:189], v[218:221], v[40:43]
	v_mfma_f32_16x16x32_bf16 v[36:39], v[178:181], v[226:229], v[36:39]
	v_mfma_f32_16x16x32_bf16 v[32:35], v[186:189], v[226:229], v[32:35]
	v_mfma_f32_16x16x32_bf16 v[60:63], v[182:185], v[206:209], v[60:63]
	v_mfma_f32_16x16x32_bf16 v[56:59], v[192:195], v[206:209], v[56:59]
	v_mfma_f32_16x16x32_bf16 v[52:55], v[182:185], v[214:217], v[52:55]
	v_mfma_f32_16x16x32_bf16 v[48:51], v[192:195], v[214:217], v[48:51]
	v_mfma_f32_16x16x32_bf16 v[44:47], v[182:185], v[222:225], v[44:47]
	v_mfma_f32_16x16x32_bf16 v[40:43], v[192:195], v[222:225], v[40:43]
	v_mfma_f32_16x16x32_bf16 v[36:39], v[182:185], v[230:233], v[36:39]
	v_mfma_f32_16x16x32_bf16 v[32:35], v[192:195], v[230:233], v[32:35]
	s_barrier
; #define PG8_STAGE(bufoff, gbase, voff) do { _Pragma("unroll") for (int _i = 0; _i < 2; ++_i) \
;         __builtin_amdgcn_global_load_lds((const unsigned*)((const char*)(gbase) + (voff)[_i]), (LAS unsigned*)(lds + (bufoff) + ldsw + _i * 8192), 16, 0, 0); } while (0)
; #define PG8_LDA(dst, b, h) do { _Pragma("unroll") for (int m = 0; m < 4; ++m) _Pragma("unroll") for (int k = 0; k < 2; ++k) dst[m][k] = *(const LAS bf16x8*)(lds + PG8_SA(b, h) + aoff + m * 2048 + k * 1024); } while (0)
; #define PG8_MMA(ai, bj, At, Bt) do { __builtin_amdgcn_s_setprio(1); _Pragma("unroll") for (int m = 0; m < 4; ++m) _Pragma("unroll") for (int n = 0; n < 2; ++n) _Pragma("unroll") for (int k = 0; k < 2; ++k) \
;         acc[ai][bj][m][n] = __builtin_amdgcn_mfma_f32_16x16x32_bf16(Bt[n][k], At[m][k], acc[ai][bj][m][n], 0, 0, 0); __builtin_amdgcn_s_setprio(0); } while (0)
; #define PG8_WAIT_V(n) asm volatile("s_waitcnt vmcnt(" #n ")" ::: "memory")
; #define PG8_WAIT_L(n) asm volatile("s_waitcnt lgkmcnt(" #n ")" ::: "memory")
; #define PG8_BAR __builtin_amdgcn_s_barrier()
; #define PG8_SCHED __builtin_amdgcn_sched_barrier(0)
; template <class Epi>
; DI void gemm_phase(LAS unsigned char* lds, const Gemm g, const Order& S, const Epi& E, const int wv) {
;     ...
;             PG8_LDA(At, 1, 1); PG8_STAGE(PG8_SB(1, 0), b3, voffB); PG8_STAGE(PG8_SB(1, 1), b3 + hstep, voffB); PG8_STAGE(PG8_SA(1, 0), a3, voffA);
;             PG8_WAIT_V(8); PG8_WAIT_L(0); PG8_BAR; PG8_MMA(1, 0, At, B0); PG8_MMA(1, 1, At, B1); PG8_BAR; PG8_SCHED;
;         }
;         if (wr == 0) PG8_BAR;
	s_add_i32 s20, s27, s50
	v_lshl_add_u64 v[152:153], v[152:153], 0, s[52:53]
	s_mov_b32 m0, s20
	ds_read_b128 v[196:199], v205 offset:49152
	ds_read_b128 v[206:209], v205 offset:50176
	ds_read_b128 v[210:213], v205 offset:51200
	ds_read_b128 v[214:217], v205 offset:52224
	ds_read_b128 v[218:221], v205 offset:53248
	ds_read_b128 v[222:225], v205 offset:54272
	ds_read_b128 v[226:229], v205 offset:55296
	ds_read_b128 v[230:233], v205 offset:56320
	global_load_lds_dwordx4 v[152:153], off
	s_add_i32 m0, s20, 0x2000
	s_add_u32 s18, s18, 0x100080
	v_lshl_add_u64 v[152:153], v[234:235], 0, s[52:53]
	s_addc_u32 s19, s19, 0
	s_add_i32 s20, s47, s50
	global_load_lds_dwordx4 v[152:153], off
	v_lshl_add_u64 v[152:153], s[18:19], 0, v[112:113]
	s_mov_b32 m0, s20
	s_nop 0
	global_load_lds_dwordx4 v[152:153], off
	v_lshl_add_u64 v[152:153], s[18:19], 0, v[146:147]
	s_add_i32 m0, s20, 0x2000
	s_nop 0
	global_load_lds_dwordx4 v[152:153], off
	v_lshl_add_u64 v[152:153], v[236:237], 0, s[52:53]
	s_mov_b32 m0, s37
	s_nop 0
	global_load_lds_dwordx4 v[152:153], off
	v_lshl_add_u64 v[152:153], v[238:239], 0, s[52:53]
	s_mov_b32 m0, s38
	s_nop 0
	global_load_lds_dwordx4 v[152:153], off
	s_waitcnt vmcnt(8)
	s_waitcnt lgkmcnt(0)
	s_barrier
	s_waitcnt lgkmcnt(0)
	v_mfma_f32_16x16x32_bf16 v[92:95], v[130:133], v[196:199], v[92:95]
	v_mfma_f32_16x16x32_bf16 v[88:91], v[138:141], v[196:199], v[88:91]
	v_mfma_f32_16x16x32_bf16 v[84:87], v[130:133], v[210:213], v[84:87]
	v_mfma_f32_16x16x32_bf16 v[80:83], v[138:141], v[210:213], v[80:83]
	v_mfma_f32_16x16x32_bf16 v[76:79], v[130:133], v[218:221], v[76:79]
	v_mfma_f32_16x16x32_bf16 v[72:75], v[138:141], v[218:221], v[72:75]
	v_mfma_f32_16x16x32_bf16 v[68:71], v[130:133], v[226:229], v[68:71]
	v_mfma_f32_16x16x32_bf16 v[64:67], v[138:141], v[226:229], v[64:67]
	v_mfma_f32_16x16x32_bf16 v[92:95], v[134:137], v[206:209], v[92:95]
	v_mfma_f32_16x16x32_bf16 v[88:91], v[174:177], v[206:209], v[88:91]
	v_mfma_f32_16x16x32_bf16 v[84:87], v[134:137], v[214:217], v[84:87]
	v_mfma_f32_16x16x32_bf16 v[80:83], v[174:177], v[214:217], v[80:83]
	v_mfma_f32_16x16x32_bf16 v[76:79], v[134:137], v[222:225], v[76:79]
	v_mfma_f32_16x16x32_bf16 v[72:75], v[174:177], v[222:225], v[72:75]
	v_mfma_f32_16x16x32_bf16 v[68:71], v[134:137], v[230:233], v[68:71]
	v_mfma_f32_16x16x32_bf16 v[64:67], v[174:177], v[230:233], v[64:67]
	v_mfma_f32_16x16x32_bf16 v[28:31], v[178:181], v[196:199], v[28:31]
	v_mfma_f32_16x16x32_bf16 v[24:27], v[186:189], v[196:199], v[24:27]
	v_mfma_f32_16x16x32_bf16 v[20:23], v[178:181], v[210:213], v[20:23]
	v_mfma_f32_16x16x32_bf16 v[16:19], v[186:189], v[210:213], v[16:19]
	v_mfma_f32_16x16x32_bf16 v[12:15], v[178:181], v[218:221], v[12:15]
	v_mfma_f32_16x16x32_bf16 v[8:11], v[186:189], v[218:221], v[8:11]
	v_mfma_f32_16x16x32_bf16 v[4:7], v[178:181], v[226:229], v[4:7]
	v_mfma_f32_16x16x32_bf16 v[0:3], v[186:189], v[226:229], v[0:3]
	v_mfma_f32_16x16x32_bf16 v[28:31], v[182:185], v[206:209], v[28:31]
	v_mfma_f32_16x16x32_bf16 v[24:27], v[192:195], v[206:209], v[24:27]
	v_mfma_f32_16x16x32_bf16 v[20:23], v[182:185], v[214:217], v[20:23]
	v_mfma_f32_16x16x32_bf16 v[16:19], v[192:195], v[214:217], v[16:19]
	v_mfma_f32_16x16x32_bf16 v[12:15], v[182:185], v[222:225], v[12:15]
	v_mfma_f32_16x16x32_bf16 v[8:11], v[192:195], v[222:225], v[8:11]
	v_mfma_f32_16x16x32_bf16 v[4:7], v[182:185], v[230:233], v[4:7]
	v_mfma_f32_16x16x32_bf16 v[0:3], v[192:195], v[230:233], v[0:3]
	s_barrier
	s_add_u32 s16, s16, 0x100
	s_addc_u32 s17, s17, 0
	s_add_u32 s24, s24, 0x100
	s_addc_u32 s25, s25, 0
	s_cmp_ge_u32 s26, s22
	s_mov_b32 s18, s26
	s_cbranch_scc0 .LBB0_989
	v_readlane_b32 s16, v253, 24
	v_readlane_b32 s17, v253, 25
	s_and_b64 vcc, exec, s[16:17]
	s_cbranch_vccz .LBB0_992
	s_barrier
